# GEMM MFMA order b,n,m,k + setprio pairs removed + forget_logits batching + x-loop counted wait + gain-max loop batched
# baseline (speedup 1.0000x reference)
; #define PG8_STAGE(bufoff, gbase, voff) do { _Pragma("unroll") for (int _i = 0; _i < 2; ++_i) \
;         __builtin_amdgcn_global_load_lds((const unsigned*)((const char*)(gbase) + (voff)[_i]), (PG8_LAS unsigned*)(lds + (bufoff) + ldsw + _i * 8192), 16, 0, 0); } while (0)
; #define PG8_LDA(dst, b, h) do { _Pragma("unroll") for (int m = 0; m < 4; ++m) _Pragma("unroll") for (int k = 0; k < 2; ++k) dst[m][k] = *(const PG8_LAS bf16x8*)(lds + PG8_SA(b, h) + aoff + m * 2048 + k * 1024); } while (0)
; #define PG8_LDB(dst, b, h) do { _Pragma("unroll") for (int n = 0; n < 2; ++n) _Pragma("unroll") for (int k = 0; k < 2; ++k) dst[n][k] = *(const PG8_LAS bf16x8*)(lds + PG8_SB(b, h) + boff + n * 2048 + k * 1024); } while (0)
; #define PG8_MMA(ai, bj, At, Bt) do { __builtin_amdgcn_s_setprio(1); _Pragma("unroll") for (int m = 0; m < 4; ++m) _Pragma("unroll") for (int n = 0; n < 2; ++n) _Pragma("unroll") for (int k = 0; k < 2; ++k) \
;         acc[ai][bj][m][n] = __builtin_amdgcn_mfma_f32_16x16x32_bf16(Bt[n][k], At[m][k], acc[ai][bj][m][n], 0, 0, 0); __builtin_amdgcn_s_setprio(0); } while (0)
; #define PG8_WAIT_V(n) asm volatile("s_waitcnt vmcnt(" #n ")" ::: "memory")
; #define PG8_WAIT_L(n) asm volatile("s_waitcnt lgkmcnt(" #n ")" ::: "memory")
; template <class Epi, class Sched, bool ALIGN_EPI = false, bool SP2 = false>
; __device__ __forceinline__ void gemm_phase(PG8_LAS unsigned char* lds, const Gemm g, const Sched& S, const Epi& E) {
;     ...
;             const bool last = (t == nt - 2);
;             const char* a1 = cA + (size_t)(t + 1) * kstep;
;             const char* a2 = last ? nA : cA + (size_t)(t + 2) * kstep; const char* b2 = last ? nB : cB + (size_t)(t + 2) * kstep;
;             const char* a3 = a2 + kstep; const char* b3 = b2 + kstep;
;             if (last && has_next) S.a_ready(nxt);
;             if constexpr (SP2) {
;             PG8_LDB(B0, 0, 0); PG8_LDB(B1, 0, 1); PG8_SCHED; PG8_LDA(At, 0, 0); PG8_STAGE(PG8_SA(1, 1), a1 + hstep, voffA);
;             PG8_WAIT_V(8); PG8_WAIT_L(0); PG8_BAR; PG8_MMA(0, 0, At, B0); PG8_MMA(0, 1, At, B1); PG8_BAR; PG8_SCHED;
;             PG8_LDA(At, 0, 1); PG8_STAGE(PG8_SB(0, 0), b2, voffB); PG8_STAGE(PG8_SB(0, 1), b2 + hstep, voffB); PG8_STAGE(PG8_SA(0, 0), a2, voffA);
;             PG8_WAIT_V(8); PG8_WAIT_L(0); PG8_BAR; PG8_MMA(1, 0, At, B0); PG8_MMA(1, 1, At, B1); PG8_BAR; PG8_SCHED;
.LBB0_132:
	s_add_u32 s18, s46, 0xfffc0080
	s_addc_u32 s38, s47, -1
	s_add_i32 s39, 0, 0x10000
	s_cmp_eq_u32 s85, 12
	s_cselect_b32 s81, s33, s38
	s_cselect_b32 s80, s73, s18
	v_add_u32_e32 v0, s39, v176
	s_cselect_b32 s45, s75, s84
	s_cselect_b32 s44, s82, s83
	s_add_i32 s18, 0, 0x14000
	ds_read_b128 v[144:147], v0
	ds_read_b128 v[148:151], v0 offset:1024
	ds_read_b128 v[152:155], v0 offset:2048
	ds_read_b128 v[156:159], v0 offset:3072
	v_add_u32_e32 v0, s18, v176
	ds_read_b128 v[160:163], v0
	ds_read_b128 v[164:167], v0 offset:1024
	ds_read_b128 v[168:171], v0 offset:2048
	ds_read_b128 v[172:175], v0 offset:3072
	v_lshl_add_u64 v[218:219], s[46:47], 0, v[140:141]
	s_add_i32 m0, s92, 0xc000
	ds_read_b128 v[180:183], v178
	ds_read_b128 v[184:187], v178 offset:1024
	ds_read_b128 v[188:191], v178 offset:2048
	ds_read_b128 v[192:195], v178 offset:3072
	ds_read_b128 v[202:205], v178 offset:4096
	ds_read_b128 v[206:209], v178 offset:5120
	ds_read_b128 v[210:213], v178 offset:6144
	ds_read_b128 v[214:217], v178 offset:7168
	global_load_lds_dwordx4 v[218:219], off
	v_lshl_add_u64 v[218:219], s[46:47], 0, v[142:143]
	s_add_i32 m0, s92, 0xe000
	s_nop 0
	global_load_lds_dwordx4 v[218:219], off
	s_waitcnt vmcnt(8)
	s_waitcnt lgkmcnt(0)
	s_barrier
	s_setprio 1
	s_waitcnt lgkmcnt(0)
	v_mfma_f32_16x16x32_bf16 v[118:121], v[144:147], v[180:183], v[118:121]
	v_mfma_f32_16x16x32_bf16 v[118:121], v[148:151], v[184:187], v[118:121]
	v_mfma_f32_16x16x32_bf16 v[102:105], v[144:147], v[188:191], v[102:105]
	v_mfma_f32_16x16x32_bf16 v[102:105], v[148:151], v[192:195], v[102:105]
	v_mfma_f32_16x16x32_bf16 v[86:89], v[144:147], v[202:205], v[86:89]
	v_mfma_f32_16x16x32_bf16 v[86:89], v[148:151], v[206:209], v[86:89]
	v_mfma_f32_16x16x32_bf16 v[70:73], v[144:147], v[210:213], v[70:73]
	v_mfma_f32_16x16x32_bf16 v[70:73], v[148:151], v[214:217], v[70:73]
	v_mfma_f32_16x16x32_bf16 v[114:117], v[152:155], v[180:183], v[114:117]
	v_mfma_f32_16x16x32_bf16 v[114:117], v[156:159], v[184:187], v[114:117]
	v_mfma_f32_16x16x32_bf16 v[98:101], v[152:155], v[188:191], v[98:101]
	v_mfma_f32_16x16x32_bf16 v[98:101], v[156:159], v[192:195], v[98:101]
	v_mfma_f32_16x16x32_bf16 v[82:85], v[152:155], v[202:205], v[82:85]
	v_mfma_f32_16x16x32_bf16 v[82:85], v[156:159], v[206:209], v[82:85]
	v_mfma_f32_16x16x32_bf16 v[66:69], v[152:155], v[210:213], v[66:69]
	v_mfma_f32_16x16x32_bf16 v[66:69], v[156:159], v[214:217], v[66:69]
	v_mfma_f32_16x16x32_bf16 v[126:129], v[160:163], v[180:183], v[126:129]
	v_mfma_f32_16x16x32_bf16 v[126:129], v[164:167], v[184:187], v[126:129]
	v_mfma_f32_16x16x32_bf16 v[110:113], v[160:163], v[188:191], v[110:113]
	v_mfma_f32_16x16x32_bf16 v[110:113], v[164:167], v[192:195], v[110:113]
	v_mfma_f32_16x16x32_bf16 v[94:97], v[160:163], v[202:205], v[94:97]
	v_mfma_f32_16x16x32_bf16 v[94:97], v[164:167], v[206:209], v[94:97]
	v_mfma_f32_16x16x32_bf16 v[78:81], v[160:163], v[210:213], v[78:81]
	v_mfma_f32_16x16x32_bf16 v[78:81], v[164:167], v[214:217], v[78:81]
	v_mfma_f32_16x16x32_bf16 v[122:125], v[168:171], v[180:183], v[122:125]
	v_mfma_f32_16x16x32_bf16 v[122:125], v[172:175], v[184:187], v[122:125]
	v_mfma_f32_16x16x32_bf16 v[106:109], v[168:171], v[188:191], v[106:109]
	v_mfma_f32_16x16x32_bf16 v[106:109], v[172:175], v[192:195], v[106:109]
	v_mfma_f32_16x16x32_bf16 v[90:93], v[168:171], v[202:205], v[90:93]
	v_mfma_f32_16x16x32_bf16 v[90:93], v[172:175], v[206:209], v[90:93]
	v_mfma_f32_16x16x32_bf16 v[74:77], v[168:171], v[210:213], v[74:77]
	v_mfma_f32_16x16x32_bf16 v[74:77], v[172:175], v[214:217], v[74:77]
	s_setprio 0
	s_barrier
	s_add_i32 s38, s39, s91
	v_lshl_add_u64 v[218:219], s[44:45], 0, v[134:135]
	s_mov_b32 m0, s38
	ds_read_b128 v[180:183], v178 offset:16384
	ds_read_b128 v[184:187], v178 offset:17408
	ds_read_b128 v[188:191], v178 offset:18432
	ds_read_b128 v[192:195], v178 offset:19456
	ds_read_b128 v[202:205], v178 offset:20480
	ds_read_b128 v[206:209], v178 offset:21504
	ds_read_b128 v[210:213], v178 offset:22528
	ds_read_b128 v[214:217], v178 offset:23552
	global_load_lds_dwordx4 v[218:219], off
	s_add_i32 m0, s38, 0x2000
	s_add_u32 s38, s44, 0x40000
	v_lshl_add_u64 v[220:221], s[44:45], 0, v[130:131]
	s_addc_u32 s39, s45, 0
	s_add_i32 s18, s18, s91
	global_load_lds_dwordx4 v[220:221], off
	v_lshl_add_u64 v[222:223], s[38:39], 0, v[134:135]
	s_mov_b32 m0, s18
	v_lshl_add_u64 v[224:225], s[80:81], 0, v[132:133]
	global_load_lds_dwordx4 v[222:223], off
	v_lshl_add_u64 v[222:223], s[38:39], 0, v[130:131]
	s_add_i32 m0, s18, 0x2000
	s_nop 0
	global_load_lds_dwordx4 v[222:223], off
	v_lshl_add_u64 v[222:223], s[80:81], 0, v[136:137]
	s_mov_b32 m0, s92
	s_nop 0
	global_load_lds_dwordx4 v[222:223], off
	s_mov_b32 m0, s93
	s_nop 0
	global_load_lds_dwordx4 v[224:225], off
	s_waitcnt vmcnt(8)
	s_waitcnt lgkmcnt(0)
	s_barrier
; #define PG8_STAGE(bufoff, gbase, voff) do { _Pragma("unroll") for (int _i = 0; _i < 2; ++_i) \
;         __builtin_amdgcn_global_load_lds((const unsigned*)((const char*)(gbase) + (voff)[_i]), (PG8_LAS unsigned*)(lds + (bufoff) + ldsw + _i * 8192), 16, 0, 0); } while (0)
; #define PG8_LDA(dst, b, h) do { _Pragma("unroll") for (int m = 0; m < 4; ++m) _Pragma("unroll") for (int k = 0; k < 2; ++k) dst[m][k] = *(const PG8_LAS bf16x8*)(lds + PG8_SA(b, h) + aoff + m * 2048 + k * 1024); } while (0)
; #define PG8_LDB(dst, b, h) do { _Pragma("unroll") for (int n = 0; n < 2; ++n) _Pragma("unroll") for (int k = 0; k < 2; ++k) dst[n][k] = *(const PG8_LAS bf16x8*)(lds + PG8_SB(b, h) + boff + n * 2048 + k * 1024); } while (0)
; #define PG8_MMA(ai, bj, At, Bt) do { __builtin_amdgcn_s_setprio(1); _Pragma("unroll") for (int m = 0; m < 4; ++m) _Pragma("unroll") for (int n = 0; n < 2; ++n) _Pragma("unroll") for (int k = 0; k < 2; ++k) \
;         acc[ai][bj][m][n] = __builtin_amdgcn_mfma_f32_16x16x32_bf16(Bt[n][k], At[m][k], acc[ai][bj][m][n], 0, 0, 0); __builtin_amdgcn_s_setprio(0); } while (0)
; #define PG8_WAIT_V(n) asm volatile("s_waitcnt vmcnt(" #n ")" ::: "memory")
; #define PG8_WAIT_L(n) asm volatile("s_waitcnt lgkmcnt(" #n ")" ::: "memory")
; #define PG8_BAR __builtin_amdgcn_s_barrier()
; #define PG8_SCHED __builtin_amdgcn_sched_barrier(0)
; template <class Epi, class Sched, bool ALIGN_EPI = false, bool SP2 = false>
; __device__ __forceinline__ void gemm_phase(PG8_LAS unsigned char* lds, const Gemm g, const Sched& S, const Epi& E) {
;     ...
;             PG8_WAIT_V(8); PG8_WAIT_L(0); PG8_BAR; PG8_MMA(1, 0, At, B0); PG8_MMA(1, 1, At, B1); PG8_BAR; PG8_SCHED;
;             PG8_LDB(B0, 1, 0); PG8_LDB(B1, 1, 1); PG8_SCHED; PG8_LDA(At, 1, 0); PG8_STAGE(PG8_SA(0, 1), a2 + hstep, voffA);
;             PG8_WAIT_V(8); PG8_WAIT_L(0); PG8_BAR; PG8_MMA(0, 0, At, B0); PG8_MMA(0, 1, At, B1); PG8_BAR; PG8_SCHED;
	s_setprio 1
	s_waitcnt lgkmcnt(0)
	v_mfma_f32_16x16x32_bf16 v[54:57], v[144:147], v[180:183], v[54:57]
	v_mfma_f32_16x16x32_bf16 v[54:57], v[148:151], v[184:187], v[54:57]
	v_mfma_f32_16x16x32_bf16 v[38:41], v[144:147], v[188:191], v[38:41]
	v_mfma_f32_16x16x32_bf16 v[38:41], v[148:151], v[192:195], v[38:41]
	v_mfma_f32_16x16x32_bf16 v[22:25], v[144:147], v[202:205], v[22:25]
	v_mfma_f32_16x16x32_bf16 v[22:25], v[148:151], v[206:209], v[22:25]
	v_mfma_f32_16x16x32_bf16 v[6:9], v[144:147], v[210:213], v[6:9]
	v_mfma_f32_16x16x32_bf16 v[6:9], v[148:151], v[214:217], v[6:9]
	v_mfma_f32_16x16x32_bf16 v[50:53], v[152:155], v[180:183], v[50:53]
	v_mfma_f32_16x16x32_bf16 v[50:53], v[156:159], v[184:187], v[50:53]
	v_mfma_f32_16x16x32_bf16 v[34:37], v[152:155], v[188:191], v[34:37]
	v_mfma_f32_16x16x32_bf16 v[34:37], v[156:159], v[192:195], v[34:37]
	v_mfma_f32_16x16x32_bf16 v[18:21], v[152:155], v[202:205], v[18:21]
	v_mfma_f32_16x16x32_bf16 v[18:21], v[156:159], v[206:209], v[18:21]
	v_mfma_f32_16x16x32_bf16 v[2:5], v[152:155], v[210:213], v[2:5]
	v_mfma_f32_16x16x32_bf16 v[2:5], v[156:159], v[214:217], v[2:5]
	v_mfma_f32_16x16x32_bf16 v[62:65], v[160:163], v[180:183], v[62:65]
	v_mfma_f32_16x16x32_bf16 v[62:65], v[164:167], v[184:187], v[62:65]
	v_mfma_f32_16x16x32_bf16 v[46:49], v[160:163], v[188:191], v[46:49]
	v_mfma_f32_16x16x32_bf16 v[46:49], v[164:167], v[192:195], v[46:49]
	v_mfma_f32_16x16x32_bf16 v[30:33], v[160:163], v[202:205], v[30:33]
	v_mfma_f32_16x16x32_bf16 v[30:33], v[164:167], v[206:209], v[30:33]
	v_mfma_f32_16x16x32_bf16 v[10:13], v[160:163], v[210:213], v[10:13]
	v_mfma_f32_16x16x32_bf16 v[10:13], v[164:167], v[214:217], v[10:13]
	v_mfma_f32_16x16x32_bf16 v[58:61], v[168:171], v[180:183], v[58:61]
	v_mfma_f32_16x16x32_bf16 v[58:61], v[172:175], v[184:187], v[58:61]
	v_mfma_f32_16x16x32_bf16 v[42:45], v[168:171], v[188:191], v[42:45]
	v_mfma_f32_16x16x32_bf16 v[42:45], v[172:175], v[192:195], v[42:45]
	v_mfma_f32_16x16x32_bf16 v[26:29], v[168:171], v[202:205], v[26:29]
	v_mfma_f32_16x16x32_bf16 v[26:29], v[172:175], v[206:209], v[26:29]
	v_mfma_f32_16x16x32_bf16 v[14:17], v[168:171], v[210:213], v[14:17]
	v_mfma_f32_16x16x32_bf16 v[14:17], v[172:175], v[214:217], v[14:17]
	s_setprio 0
	s_barrier
	s_add_i32 s18, 0, 0x18000
	v_add_u32_e32 v0, s18, v176
	s_add_i32 vcc_lo, 0, 0x1c000
	ds_read_b128 v[144:147], v0
	ds_read_b128 v[148:151], v0 offset:1024
	ds_read_b128 v[152:155], v0 offset:2048
	ds_read_b128 v[156:159], v0 offset:3072
	v_add_u32_e32 v0, vcc_lo, v176
	ds_read_b128 v[160:163], v0
	ds_read_b128 v[164:167], v0 offset:1024
	ds_read_b128 v[168:171], v0 offset:2048
	ds_read_b128 v[172:175], v0 offset:3072
	s_add_u32 s38, s80, 0x40000
	s_addc_u32 s39, s81, 0
	s_mov_b32 m0, s94
	v_lshl_add_u64 v[226:227], s[38:39], 0, v[136:137]
	ds_read_b128 v[180:183], v178 offset:32768
	ds_read_b128 v[184:187], v178 offset:33792
	ds_read_b128 v[188:191], v178 offset:34816
	ds_read_b128 v[192:195], v178 offset:35840
	ds_read_b128 v[202:205], v178 offset:36864
	ds_read_b128 v[206:209], v178 offset:37888
	ds_read_b128 v[210:213], v178 offset:38912
	ds_read_b128 v[214:217], v178 offset:39936
	global_load_lds_dwordx4 v[226:227], off
	v_lshl_add_u64 v[226:227], s[38:39], 0, v[132:133]
	s_mov_b32 m0, s95
	s_nop 0
	global_load_lds_dwordx4 v[226:227], off
	s_waitcnt vmcnt(8)
	s_waitcnt lgkmcnt(0)
	s_barrier
	s_setprio 1
	s_waitcnt lgkmcnt(0)
	v_mfma_f32_16x16x32_bf16 v[118:121], v[144:147], v[180:183], v[118:121]
	v_mfma_f32_16x16x32_bf16 v[118:121], v[148:151], v[184:187], v[118:121]
	v_mfma_f32_16x16x32_bf16 v[102:105], v[144:147], v[188:191], v[102:105]
	v_mfma_f32_16x16x32_bf16 v[102:105], v[148:151], v[192:195], v[102:105]
	v_mfma_f32_16x16x32_bf16 v[86:89], v[144:147], v[202:205], v[86:89]
	v_mfma_f32_16x16x32_bf16 v[86:89], v[148:151], v[206:209], v[86:89]
	v_mfma_f32_16x16x32_bf16 v[70:73], v[144:147], v[210:213], v[70:73]
	v_mfma_f32_16x16x32_bf16 v[70:73], v[148:151], v[214:217], v[70:73]
	v_mfma_f32_16x16x32_bf16 v[114:117], v[152:155], v[180:183], v[114:117]
	v_mfma_f32_16x16x32_bf16 v[114:117], v[156:159], v[184:187], v[114:117]
	v_mfma_f32_16x16x32_bf16 v[98:101], v[152:155], v[188:191], v[98:101]
	v_mfma_f32_16x16x32_bf16 v[98:101], v[156:159], v[192:195], v[98:101]
	v_mfma_f32_16x16x32_bf16 v[82:85], v[152:155], v[202:205], v[82:85]
	v_mfma_f32_16x16x32_bf16 v[82:85], v[156:159], v[206:209], v[82:85]
	v_mfma_f32_16x16x32_bf16 v[66:69], v[152:155], v[210:213], v[66:69]
	v_mfma_f32_16x16x32_bf16 v[66:69], v[156:159], v[214:217], v[66:69]
	v_mfma_f32_16x16x32_bf16 v[126:129], v[160:163], v[180:183], v[126:129]
	v_mfma_f32_16x16x32_bf16 v[126:129], v[164:167], v[184:187], v[126:129]
	v_mfma_f32_16x16x32_bf16 v[110:113], v[160:163], v[188:191], v[110:113]
	v_mfma_f32_16x16x32_bf16 v[110:113], v[164:167], v[192:195], v[110:113]
	v_mfma_f32_16x16x32_bf16 v[94:97], v[160:163], v[202:205], v[94:97]
	v_mfma_f32_16x16x32_bf16 v[94:97], v[164:167], v[206:209], v[94:97]
	v_mfma_f32_16x16x32_bf16 v[78:81], v[160:163], v[210:213], v[78:81]
	v_mfma_f32_16x16x32_bf16 v[78:81], v[164:167], v[214:217], v[78:81]
	v_mfma_f32_16x16x32_bf16 v[122:125], v[168:171], v[180:183], v[122:125]
	v_mfma_f32_16x16x32_bf16 v[122:125], v[172:175], v[184:187], v[122:125]
	v_mfma_f32_16x16x32_bf16 v[106:109], v[168:171], v[188:191], v[106:109]
	v_mfma_f32_16x16x32_bf16 v[106:109], v[172:175], v[192:195], v[106:109]
	v_mfma_f32_16x16x32_bf16 v[90:93], v[168:171], v[202:205], v[90:93]
	v_mfma_f32_16x16x32_bf16 v[90:93], v[172:175], v[206:209], v[90:93]
	v_mfma_f32_16x16x32_bf16 v[74:77], v[168:171], v[210:213], v[74:77]
	v_mfma_f32_16x16x32_bf16 v[74:77], v[172:175], v[214:217], v[74:77]
	s_setprio 0
	s_barrier
; #define PG8_STAGE(bufoff, gbase, voff) do { _Pragma("unroll") for (int _i = 0; _i < 2; ++_i) \
;         __builtin_amdgcn_global_load_lds((const unsigned*)((const char*)(gbase) + (voff)[_i]), (PG8_LAS unsigned*)(lds + (bufoff) + ldsw + _i * 8192), 16, 0, 0); } while (0)
; #define PG8_LDA(dst, b, h) do { _Pragma("unroll") for (int m = 0; m < 4; ++m) _Pragma("unroll") for (int k = 0; k < 2; ++k) dst[m][k] = *(const PG8_LAS bf16x8*)(lds + PG8_SA(b, h) + aoff + m * 2048 + k * 1024); } while (0)
; #define PG8_MMA(ai, bj, At, Bt) do { __builtin_amdgcn_s_setprio(1); _Pragma("unroll") for (int m = 0; m < 4; ++m) _Pragma("unroll") for (int n = 0; n < 2; ++n) _Pragma("unroll") for (int k = 0; k < 2; ++k) \
;         acc[ai][bj][m][n] = __builtin_amdgcn_mfma_f32_16x16x32_bf16(Bt[n][k], At[m][k], acc[ai][bj][m][n], 0, 0, 0); __builtin_amdgcn_s_setprio(0); } while (0)
; #define PG8_WAIT_V(n) asm volatile("s_waitcnt vmcnt(" #n ")" ::: "memory")
; #define PG8_WAIT_L(n) asm volatile("s_waitcnt lgkmcnt(" #n ")" ::: "memory")
; #define PG8_BAR __builtin_amdgcn_s_barrier()
; #define PG8_SCHED __builtin_amdgcn_sched_barrier(0)
; template <class Epi, class Sched, bool ALIGN_EPI = false, bool SP2 = false>
; __device__ __forceinline__ void gemm_phase(PG8_LAS unsigned char* lds, const Gemm g, const Sched& S, const Epi& E) {
;     ...
;             PG8_LDA(At, 1, 1); PG8_STAGE(PG8_SB(1, 0), b3, voffB); PG8_STAGE(PG8_SB(1, 1), b3 + hstep, voffB); PG8_STAGE(PG8_SA(1, 0), a3, voffA);
;             PG8_WAIT_V(8); PG8_WAIT_L(0); PG8_BAR; PG8_MMA(1, 0, At, B0); PG8_MMA(1, 1, At, B1); PG8_BAR; PG8_SCHED;
	s_add_i32 s18, s18, s91
	v_lshl_add_u64 v[218:219], v[218:219], 0, s[30:31]
	s_mov_b32 m0, s18
	ds_read_b128 v[180:183], v178 offset:49152
	ds_read_b128 v[184:187], v178 offset:50176
	ds_read_b128 v[188:191], v178 offset:51200
	ds_read_b128 v[192:195], v178 offset:52224
	ds_read_b128 v[202:205], v178 offset:53248
	ds_read_b128 v[206:209], v178 offset:54272
	ds_read_b128 v[210:213], v178 offset:55296
	ds_read_b128 v[214:217], v178 offset:56320
	global_load_lds_dwordx4 v[218:219], off
	s_add_i32 m0, s18, 0x2000
	s_add_u32 s38, s44, 0x40080
	v_lshl_add_u64 v[218:219], v[220:221], 0, s[30:31]
	s_addc_u32 s39, s45, 0
	s_add_i32 s18, vcc_lo, s91
	global_load_lds_dwordx4 v[218:219], off
	v_lshl_add_u64 v[218:219], s[38:39], 0, v[134:135]
	s_mov_b32 m0, s18
	s_nop 0
	global_load_lds_dwordx4 v[218:219], off
	v_lshl_add_u64 v[218:219], s[38:39], 0, v[130:131]
	s_add_i32 m0, s18, 0x2000
	s_nop 0
	global_load_lds_dwordx4 v[218:219], off
	v_lshl_add_u64 v[218:219], v[222:223], 0, s[30:31]
	s_mov_b32 m0, s7
	s_nop 0
	global_load_lds_dwordx4 v[218:219], off
	v_lshl_add_u64 v[218:219], v[224:225], 0, s[30:31]
	s_mov_b32 m0, s96
	s_nop 0
	global_load_lds_dwordx4 v[218:219], off
	s_waitcnt vmcnt(8)
	s_waitcnt lgkmcnt(0)
	s_barrier
	s_setprio 1
	s_waitcnt lgkmcnt(0)
	v_mfma_f32_16x16x32_bf16 v[54:57], v[144:147], v[180:183], v[54:57]
	v_mfma_f32_16x16x32_bf16 v[54:57], v[148:151], v[184:187], v[54:57]
	v_mfma_f32_16x16x32_bf16 v[38:41], v[144:147], v[188:191], v[38:41]
	v_mfma_f32_16x16x32_bf16 v[38:41], v[148:151], v[192:195], v[38:41]
	v_mfma_f32_16x16x32_bf16 v[22:25], v[144:147], v[202:205], v[22:25]
	v_mfma_f32_16x16x32_bf16 v[22:25], v[148:151], v[206:209], v[22:25]
	v_mfma_f32_16x16x32_bf16 v[6:9], v[144:147], v[210:213], v[6:9]
	v_mfma_f32_16x16x32_bf16 v[6:9], v[148:151], v[214:217], v[6:9]
	v_mfma_f32_16x16x32_bf16 v[50:53], v[152:155], v[180:183], v[50:53]
	v_mfma_f32_16x16x32_bf16 v[50:53], v[156:159], v[184:187], v[50:53]
	v_mfma_f32_16x16x32_bf16 v[34:37], v[152:155], v[188:191], v[34:37]
	v_mfma_f32_16x16x32_bf16 v[34:37], v[156:159], v[192:195], v[34:37]
	v_mfma_f32_16x16x32_bf16 v[18:21], v[152:155], v[202:205], v[18:21]
	v_mfma_f32_16x16x32_bf16 v[18:21], v[156:159], v[206:209], v[18:21]
	v_mfma_f32_16x16x32_bf16 v[2:5], v[152:155], v[210:213], v[2:5]
	v_mfma_f32_16x16x32_bf16 v[2:5], v[156:159], v[214:217], v[2:5]
	v_mfma_f32_16x16x32_bf16 v[62:65], v[160:163], v[180:183], v[62:65]
	v_mfma_f32_16x16x32_bf16 v[62:65], v[164:167], v[184:187], v[62:65]
	v_mfma_f32_16x16x32_bf16 v[46:49], v[160:163], v[188:191], v[46:49]
	v_mfma_f32_16x16x32_bf16 v[46:49], v[164:167], v[192:195], v[46:49]
	v_mfma_f32_16x16x32_bf16 v[30:33], v[160:163], v[202:205], v[30:33]
	v_mfma_f32_16x16x32_bf16 v[30:33], v[164:167], v[206:209], v[30:33]
	v_mfma_f32_16x16x32_bf16 v[10:13], v[160:163], v[210:213], v[10:13]
	v_mfma_f32_16x16x32_bf16 v[10:13], v[164:167], v[214:217], v[10:13]
	v_mfma_f32_16x16x32_bf16 v[58:61], v[168:171], v[180:183], v[58:61]
	v_mfma_f32_16x16x32_bf16 v[58:61], v[172:175], v[184:187], v[58:61]
	v_mfma_f32_16x16x32_bf16 v[42:45], v[168:171], v[188:191], v[42:45]
	v_mfma_f32_16x16x32_bf16 v[42:45], v[172:175], v[192:195], v[42:45]
	v_mfma_f32_16x16x32_bf16 v[26:29], v[168:171], v[202:205], v[26:29]
	v_mfma_f32_16x16x32_bf16 v[26:29], v[172:175], v[206:209], v[26:29]
	v_mfma_f32_16x16x32_bf16 v[14:17], v[168:171], v[210:213], v[14:17]
	v_mfma_f32_16x16x32_bf16 v[14:17], v[172:175], v[214:217], v[14:17]
	s_setprio 0
	s_barrier
	s_add_i32 s85, s85, 2
	s_add_u32 s46, s46, 0x100
	s_addc_u32 s47, s47, 0
	s_add_u32 s83, s83, 0x100
	s_addc_u32 s84, s84, 0
	s_cmp_gt_u32 s85, 13
	s_cbranch_scc0 .LBB0_132
	s_and_b64 vcc, exec, s[10:11]
	s_cbranch_vccz .LBB0_135
	s_barrier

; #define PG8_STAGE(bufoff, gbase, voff) do { _Pragma("unroll") for (int _i = 0; _i < 2; ++_i) \
;         __builtin_amdgcn_global_load_lds((const unsigned*)((const char*)(gbase) + (voff)[_i]), (PG8_LAS unsigned*)(lds + (bufoff) + ldsw + _i * 8192), 16, 0, 0); } while (0)
; #define PG8_LDA(dst, b, h) do { _Pragma("unroll") for (int m = 0; m < 4; ++m) _Pragma("unroll") for (int k = 0; k < 2; ++k) dst[m][k] = *(const PG8_LAS bf16x8*)(lds + PG8_SA(b, h) + aoff + m * 2048 + k * 1024); } while (0)
; #define PG8_LDB(dst, b, h) do { _Pragma("unroll") for (int n = 0; n < 2; ++n) _Pragma("unroll") for (int k = 0; k < 2; ++k) dst[n][k] = *(const PG8_LAS bf16x8*)(lds + PG8_SB(b, h) + boff + n * 2048 + k * 1024); } while (0)
; #define PG8_MMA(ai, bj, At, Bt) do { __builtin_amdgcn_s_setprio(1); _Pragma("unroll") for (int m = 0; m < 4; ++m) _Pragma("unroll") for (int n = 0; n < 2; ++n) _Pragma("unroll") for (int k = 0; k < 2; ++k) \
;         acc[ai][bj][m][n] = __builtin_amdgcn_mfma_f32_16x16x32_bf16(Bt[n][k], At[m][k], acc[ai][bj][m][n], 0, 0, 0); __builtin_amdgcn_s_setprio(0); } while (0)
; #define PG8_WAIT_V(n) asm volatile("s_waitcnt vmcnt(" #n ")" ::: "memory")
; #define PG8_WAIT_L(n) asm volatile("s_waitcnt lgkmcnt(" #n ")" ::: "memory")
; template <class Epi, class Sched, bool ALIGN_EPI = false, bool SP2 = false>
; __device__ __forceinline__ void gemm_phase(PG8_LAS unsigned char* lds, const Gemm g, const Sched& S, const Epi& E) {
;     ...
;             const bool last = (t == nt - 2);
;             const char* a1 = cA + (size_t)(t + 1) * kstep;
;             const char* a2 = last ? nA : cA + (size_t)(t + 2) * kstep; const char* b2 = last ? nB : cB + (size_t)(t + 2) * kstep;
;             const char* a3 = a2 + kstep; const char* b3 = b2 + kstep;
;             if (last && has_next) S.a_ready(nxt);
;             if constexpr (SP2) {
;             PG8_LDB(B0, 0, 0); PG8_LDB(B1, 0, 1); PG8_SCHED; PG8_LDA(At, 0, 0); PG8_STAGE(PG8_SA(1, 1), a1 + hstep, voffA);
;             PG8_WAIT_V(8); PG8_WAIT_L(0); PG8_BAR; PG8_MMA(0, 0, At, B0); PG8_MMA(0, 1, At, B1); PG8_BAR; PG8_SCHED;
;             PG8_LDA(At, 0, 1); PG8_STAGE(PG8_SB(0, 0), b2, voffB); PG8_STAGE(PG8_SB(0, 1), b2 + hstep, voffB); PG8_STAGE(PG8_SA(0, 0), a2, voffA);
;             PG8_WAIT_V(8); PG8_WAIT_L(0); PG8_BAR; PG8_MMA(1, 0, At, B0); PG8_MMA(1, 1, At, B1); PG8_BAR; PG8_SCHED;
.LBB0_220:
	s_add_u32 s18, s60, 0xfffc0080
	s_addc_u32 s38, s61, -1
	s_add_i32 s39, 0, 0x10000
	s_cmp_eq_u32 s82, 12
	s_cselect_b32 s65, s47, s38
	s_cselect_b32 s64, s78, s18
	v_add_u32_e32 v145, s39, v141
	s_cselect_b32 s57, s49, s81
	s_cselect_b32 s56, s79, s80
	s_add_i32 s18, 0, 0x14000
	ds_read_b128 v[146:149], v145
	ds_read_b128 v[150:153], v145 offset:1024
	ds_read_b128 v[154:157], v145 offset:2048
	ds_read_b128 v[158:161], v145 offset:3072
	v_add_u32_e32 v145, s18, v141
	ds_read_b128 v[162:165], v145
	ds_read_b128 v[166:169], v145 offset:1024
	ds_read_b128 v[170:173], v145 offset:2048
	ds_read_b128 v[174:177], v145 offset:3072
	v_lshl_add_u64 v[194:195], s[60:61], 0, v[136:137]
	s_add_i32 m0, s29, 0xc000
	ds_read_b128 v[178:181], v144
	ds_read_b128 v[182:185], v144 offset:1024
	ds_read_b128 v[186:189], v144 offset:2048
	ds_read_b128 v[190:193], v144 offset:3072
	ds_read_b128 v[202:205], v144 offset:4096
	ds_read_b128 v[206:209], v144 offset:5120
	ds_read_b128 v[210:213], v144 offset:6144
	ds_read_b128 v[214:217], v144 offset:7168
	global_load_lds_dwordx4 v[194:195], off
	v_lshl_add_u64 v[194:195], s[60:61], 0, v[138:139]
	s_add_i32 m0, s29, 0xe000
	s_nop 0
	global_load_lds_dwordx4 v[194:195], off
	s_waitcnt vmcnt(8)
	s_waitcnt lgkmcnt(0)
	s_barrier
	s_setprio 1
	s_waitcnt lgkmcnt(0)
	v_mfma_f32_16x16x32_bf16 v[114:117], v[146:149], v[178:181], v[114:117]
	v_mfma_f32_16x16x32_bf16 v[114:117], v[150:153], v[182:185], v[114:117]
	v_mfma_f32_16x16x32_bf16 v[98:101], v[146:149], v[186:189], v[98:101]
	v_mfma_f32_16x16x32_bf16 v[98:101], v[150:153], v[190:193], v[98:101]
	v_mfma_f32_16x16x32_bf16 v[82:85], v[146:149], v[202:205], v[82:85]
	v_mfma_f32_16x16x32_bf16 v[82:85], v[150:153], v[206:209], v[82:85]
	v_mfma_f32_16x16x32_bf16 v[66:69], v[146:149], v[210:213], v[66:69]
	v_mfma_f32_16x16x32_bf16 v[66:69], v[150:153], v[214:217], v[66:69]
	v_mfma_f32_16x16x32_bf16 v[118:121], v[154:157], v[178:181], v[118:121]
	v_mfma_f32_16x16x32_bf16 v[118:121], v[158:161], v[182:185], v[118:121]
	v_mfma_f32_16x16x32_bf16 v[102:105], v[154:157], v[186:189], v[102:105]
	v_mfma_f32_16x16x32_bf16 v[102:105], v[158:161], v[190:193], v[102:105]
	v_mfma_f32_16x16x32_bf16 v[86:89], v[154:157], v[202:205], v[86:89]
	v_mfma_f32_16x16x32_bf16 v[86:89], v[158:161], v[206:209], v[86:89]
	v_mfma_f32_16x16x32_bf16 v[70:73], v[154:157], v[210:213], v[70:73]
	v_mfma_f32_16x16x32_bf16 v[70:73], v[158:161], v[214:217], v[70:73]
	v_mfma_f32_16x16x32_bf16 v[122:125], v[162:165], v[178:181], v[122:125]
	v_mfma_f32_16x16x32_bf16 v[122:125], v[166:169], v[182:185], v[122:125]
	v_mfma_f32_16x16x32_bf16 v[106:109], v[162:165], v[186:189], v[106:109]
	v_mfma_f32_16x16x32_bf16 v[106:109], v[166:169], v[190:193], v[106:109]
	v_mfma_f32_16x16x32_bf16 v[90:93], v[162:165], v[202:205], v[90:93]
	v_mfma_f32_16x16x32_bf16 v[90:93], v[166:169], v[206:209], v[90:93]
	v_mfma_f32_16x16x32_bf16 v[74:77], v[162:165], v[210:213], v[74:77]
	v_mfma_f32_16x16x32_bf16 v[74:77], v[166:169], v[214:217], v[74:77]
	v_mfma_f32_16x16x32_bf16 v[126:129], v[170:173], v[178:181], v[126:129]
	v_mfma_f32_16x16x32_bf16 v[126:129], v[174:177], v[182:185], v[126:129]
	v_mfma_f32_16x16x32_bf16 v[110:113], v[170:173], v[186:189], v[110:113]
	v_mfma_f32_16x16x32_bf16 v[110:113], v[174:177], v[190:193], v[110:113]
	v_mfma_f32_16x16x32_bf16 v[94:97], v[170:173], v[202:205], v[94:97]
	v_mfma_f32_16x16x32_bf16 v[94:97], v[174:177], v[206:209], v[94:97]
	v_mfma_f32_16x16x32_bf16 v[78:81], v[170:173], v[210:213], v[78:81]
	v_mfma_f32_16x16x32_bf16 v[78:81], v[174:177], v[214:217], v[78:81]
	s_setprio 0
	s_barrier
	s_add_i32 s38, s39, s27
	v_lshl_add_u64 v[194:195], s[56:57], 0, v[0:1]
	s_mov_b32 m0, s38
	ds_read_b128 v[178:181], v144 offset:16384
	ds_read_b128 v[182:185], v144 offset:17408
	ds_read_b128 v[186:189], v144 offset:18432
	ds_read_b128 v[190:193], v144 offset:19456
	ds_read_b128 v[202:205], v144 offset:20480
	ds_read_b128 v[206:209], v144 offset:21504
	ds_read_b128 v[210:213], v144 offset:22528
	ds_read_b128 v[214:217], v144 offset:23552
	global_load_lds_dwordx4 v[194:195], off
	s_add_i32 m0, s38, 0x2000
	s_add_u32 s38, s56, 0x40000
	v_lshl_add_u64 v[218:219], s[56:57], 0, v[130:131]
	s_addc_u32 s39, s57, 0
	s_add_i32 s18, s18, s27
	global_load_lds_dwordx4 v[218:219], off
	v_lshl_add_u64 v[220:221], s[38:39], 0, v[0:1]
	s_mov_b32 m0, s18
	v_lshl_add_u64 v[222:223], s[64:65], 0, v[132:133]
	global_load_lds_dwordx4 v[220:221], off
	v_lshl_add_u64 v[220:221], s[38:39], 0, v[130:131]
	s_add_i32 m0, s18, 0x2000
	s_nop 0
	global_load_lds_dwordx4 v[220:221], off
	v_lshl_add_u64 v[220:221], s[64:65], 0, v[134:135]
	s_mov_b32 m0, s29
	s_nop 0
	global_load_lds_dwordx4 v[220:221], off
	s_mov_b32 m0, s33
	s_nop 0
	global_load_lds_dwordx4 v[222:223], off
	s_waitcnt vmcnt(8)
	s_waitcnt lgkmcnt(0)
	s_barrier
; #define PG8_STAGE(bufoff, gbase, voff) do { _Pragma("unroll") for (int _i = 0; _i < 2; ++_i) \
;         __builtin_amdgcn_global_load_lds((const unsigned*)((const char*)(gbase) + (voff)[_i]), (PG8_LAS unsigned*)(lds + (bufoff) + ldsw + _i * 8192), 16, 0, 0); } while (0)
; #define PG8_LDA(dst, b, h) do { _Pragma("unroll") for (int m = 0; m < 4; ++m) _Pragma("unroll") for (int k = 0; k < 2; ++k) dst[m][k] = *(const PG8_LAS bf16x8*)(lds + PG8_SA(b, h) + aoff + m * 2048 + k * 1024); } while (0)
; #define PG8_LDB(dst, b, h) do { _Pragma("unroll") for (int n = 0; n < 2; ++n) _Pragma("unroll") for (int k = 0; k < 2; ++k) dst[n][k] = *(const PG8_LAS bf16x8*)(lds + PG8_SB(b, h) + boff + n * 2048 + k * 1024); } while (0)
; #define PG8_MMA(ai, bj, At, Bt) do { __builtin_amdgcn_s_setprio(1); _Pragma("unroll") for (int m = 0; m < 4; ++m) _Pragma("unroll") for (int n = 0; n < 2; ++n) _Pragma("unroll") for (int k = 0; k < 2; ++k) \
;         acc[ai][bj][m][n] = __builtin_amdgcn_mfma_f32_16x16x32_bf16(Bt[n][k], At[m][k], acc[ai][bj][m][n], 0, 0, 0); __builtin_amdgcn_s_setprio(0); } while (0)
; #define PG8_WAIT_V(n) asm volatile("s_waitcnt vmcnt(" #n ")" ::: "memory")
; #define PG8_WAIT_L(n) asm volatile("s_waitcnt lgkmcnt(" #n ")" ::: "memory")
; #define PG8_BAR __builtin_amdgcn_s_barrier()
; #define PG8_SCHED __builtin_amdgcn_sched_barrier(0)
; template <class Epi, class Sched, bool ALIGN_EPI = false, bool SP2 = false>
; __device__ __forceinline__ void gemm_phase(PG8_LAS unsigned char* lds, const Gemm g, const Sched& S, const Epi& E) {
;     ...
;             PG8_WAIT_V(8); PG8_WAIT_L(0); PG8_BAR; PG8_MMA(1, 0, At, B0); PG8_MMA(1, 1, At, B1); PG8_BAR; PG8_SCHED;
;             PG8_LDB(B0, 1, 0); PG8_LDB(B1, 1, 1); PG8_SCHED; PG8_LDA(At, 1, 0); PG8_STAGE(PG8_SA(0, 1), a2 + hstep, voffA);
;             PG8_WAIT_V(8); PG8_WAIT_L(0); PG8_BAR; PG8_MMA(0, 0, At, B0); PG8_MMA(0, 1, At, B1); PG8_BAR; PG8_SCHED;
	s_setprio 1
	s_waitcnt lgkmcnt(0)
	v_mfma_f32_16x16x32_bf16 v[50:53], v[146:149], v[178:181], v[50:53]
	v_mfma_f32_16x16x32_bf16 v[50:53], v[150:153], v[182:185], v[50:53]
	v_mfma_f32_16x16x32_bf16 v[34:37], v[146:149], v[186:189], v[34:37]
	v_mfma_f32_16x16x32_bf16 v[34:37], v[150:153], v[190:193], v[34:37]
	v_mfma_f32_16x16x32_bf16 v[18:21], v[146:149], v[202:205], v[18:21]
	v_mfma_f32_16x16x32_bf16 v[18:21], v[150:153], v[206:209], v[18:21]
	v_mfma_f32_16x16x32_bf16 v[2:5], v[146:149], v[210:213], v[2:5]
	v_mfma_f32_16x16x32_bf16 v[2:5], v[150:153], v[214:217], v[2:5]
	v_mfma_f32_16x16x32_bf16 v[54:57], v[154:157], v[178:181], v[54:57]
	v_mfma_f32_16x16x32_bf16 v[54:57], v[158:161], v[182:185], v[54:57]
	v_mfma_f32_16x16x32_bf16 v[38:41], v[154:157], v[186:189], v[38:41]
	v_mfma_f32_16x16x32_bf16 v[38:41], v[158:161], v[190:193], v[38:41]
	v_mfma_f32_16x16x32_bf16 v[22:25], v[154:157], v[202:205], v[22:25]
	v_mfma_f32_16x16x32_bf16 v[22:25], v[158:161], v[206:209], v[22:25]
	v_mfma_f32_16x16x32_bf16 v[6:9], v[154:157], v[210:213], v[6:9]
	v_mfma_f32_16x16x32_bf16 v[6:9], v[158:161], v[214:217], v[6:9]
	v_mfma_f32_16x16x32_bf16 v[58:61], v[162:165], v[178:181], v[58:61]
	v_mfma_f32_16x16x32_bf16 v[58:61], v[166:169], v[182:185], v[58:61]
	v_mfma_f32_16x16x32_bf16 v[42:45], v[162:165], v[186:189], v[42:45]
	v_mfma_f32_16x16x32_bf16 v[42:45], v[166:169], v[190:193], v[42:45]
	v_mfma_f32_16x16x32_bf16 v[26:29], v[162:165], v[202:205], v[26:29]
	v_mfma_f32_16x16x32_bf16 v[26:29], v[166:169], v[206:209], v[26:29]
	v_mfma_f32_16x16x32_bf16 v[10:13], v[162:165], v[210:213], v[10:13]
	v_mfma_f32_16x16x32_bf16 v[10:13], v[166:169], v[214:217], v[10:13]
	v_mfma_f32_16x16x32_bf16 v[62:65], v[170:173], v[178:181], v[62:65]
	v_mfma_f32_16x16x32_bf16 v[62:65], v[174:177], v[182:185], v[62:65]
	v_mfma_f32_16x16x32_bf16 v[46:49], v[170:173], v[186:189], v[46:49]
	v_mfma_f32_16x16x32_bf16 v[46:49], v[174:177], v[190:193], v[46:49]
	v_mfma_f32_16x16x32_bf16 v[30:33], v[170:173], v[202:205], v[30:33]
	v_mfma_f32_16x16x32_bf16 v[30:33], v[174:177], v[206:209], v[30:33]
	v_mfma_f32_16x16x32_bf16 v[14:17], v[170:173], v[210:213], v[14:17]
	v_mfma_f32_16x16x32_bf16 v[14:17], v[174:177], v[214:217], v[14:17]
	s_setprio 0
	s_barrier
	s_add_i32 s18, 0, 0x18000
	v_add_u32_e32 v145, s18, v141
	s_add_i32 s83, 0, 0x1c000
	ds_read_b128 v[146:149], v145
	ds_read_b128 v[150:153], v145 offset:1024
	ds_read_b128 v[154:157], v145 offset:2048
	ds_read_b128 v[158:161], v145 offset:3072
	v_add_u32_e32 v145, s83, v141
	ds_read_b128 v[162:165], v145
	ds_read_b128 v[166:169], v145 offset:1024
	ds_read_b128 v[170:173], v145 offset:2048
	ds_read_b128 v[174:177], v145 offset:3072
	s_add_u32 s38, s64, 0x40000
	s_addc_u32 s39, s65, 0
	s_mov_b32 m0, s58
	v_lshl_add_u64 v[224:225], s[38:39], 0, v[134:135]
	ds_read_b128 v[178:181], v144 offset:32768
	ds_read_b128 v[182:185], v144 offset:33792
	ds_read_b128 v[186:189], v144 offset:34816
	ds_read_b128 v[190:193], v144 offset:35840
	ds_read_b128 v[202:205], v144 offset:36864
	ds_read_b128 v[206:209], v144 offset:37888
	ds_read_b128 v[210:213], v144 offset:38912
	ds_read_b128 v[214:217], v144 offset:39936
	global_load_lds_dwordx4 v[224:225], off
	v_lshl_add_u64 v[224:225], s[38:39], 0, v[132:133]
	s_mov_b32 m0, s69
	s_nop 0
	global_load_lds_dwordx4 v[224:225], off
	s_waitcnt vmcnt(8)
	s_waitcnt lgkmcnt(0)
	s_barrier
	s_setprio 1
	s_waitcnt lgkmcnt(0)
	v_mfma_f32_16x16x32_bf16 v[114:117], v[146:149], v[178:181], v[114:117]
	v_mfma_f32_16x16x32_bf16 v[114:117], v[150:153], v[182:185], v[114:117]
	v_mfma_f32_16x16x32_bf16 v[98:101], v[146:149], v[186:189], v[98:101]
	v_mfma_f32_16x16x32_bf16 v[98:101], v[150:153], v[190:193], v[98:101]
	v_mfma_f32_16x16x32_bf16 v[82:85], v[146:149], v[202:205], v[82:85]
	v_mfma_f32_16x16x32_bf16 v[82:85], v[150:153], v[206:209], v[82:85]
	v_mfma_f32_16x16x32_bf16 v[66:69], v[146:149], v[210:213], v[66:69]
	v_mfma_f32_16x16x32_bf16 v[66:69], v[150:153], v[214:217], v[66:69]
	v_mfma_f32_16x16x32_bf16 v[118:121], v[154:157], v[178:181], v[118:121]
	v_mfma_f32_16x16x32_bf16 v[118:121], v[158:161], v[182:185], v[118:121]
	v_mfma_f32_16x16x32_bf16 v[102:105], v[154:157], v[186:189], v[102:105]
	v_mfma_f32_16x16x32_bf16 v[102:105], v[158:161], v[190:193], v[102:105]
	v_mfma_f32_16x16x32_bf16 v[86:89], v[154:157], v[202:205], v[86:89]
	v_mfma_f32_16x16x32_bf16 v[86:89], v[158:161], v[206:209], v[86:89]
	v_mfma_f32_16x16x32_bf16 v[70:73], v[154:157], v[210:213], v[70:73]
	v_mfma_f32_16x16x32_bf16 v[70:73], v[158:161], v[214:217], v[70:73]
	v_mfma_f32_16x16x32_bf16 v[122:125], v[162:165], v[178:181], v[122:125]
	v_mfma_f32_16x16x32_bf16 v[122:125], v[166:169], v[182:185], v[122:125]
	v_mfma_f32_16x16x32_bf16 v[106:109], v[162:165], v[186:189], v[106:109]
	v_mfma_f32_16x16x32_bf16 v[106:109], v[166:169], v[190:193], v[106:109]
	v_mfma_f32_16x16x32_bf16 v[90:93], v[162:165], v[202:205], v[90:93]
	v_mfma_f32_16x16x32_bf16 v[90:93], v[166:169], v[206:209], v[90:93]
	v_mfma_f32_16x16x32_bf16 v[74:77], v[162:165], v[210:213], v[74:77]
	v_mfma_f32_16x16x32_bf16 v[74:77], v[166:169], v[214:217], v[74:77]
	v_mfma_f32_16x16x32_bf16 v[126:129], v[170:173], v[178:181], v[126:129]
	v_mfma_f32_16x16x32_bf16 v[126:129], v[174:177], v[182:185], v[126:129]
	v_mfma_f32_16x16x32_bf16 v[110:113], v[170:173], v[186:189], v[110:113]
	v_mfma_f32_16x16x32_bf16 v[110:113], v[174:177], v[190:193], v[110:113]
	v_mfma_f32_16x16x32_bf16 v[94:97], v[170:173], v[202:205], v[94:97]
	v_mfma_f32_16x16x32_bf16 v[94:97], v[174:177], v[206:209], v[94:97]
	v_mfma_f32_16x16x32_bf16 v[78:81], v[170:173], v[210:213], v[78:81]
	v_mfma_f32_16x16x32_bf16 v[78:81], v[174:177], v[214:217], v[78:81]
	s_setprio 0
	s_barrier
; #define PG8_STAGE(bufoff, gbase, voff) do { _Pragma("unroll") for (int _i = 0; _i < 2; ++_i) \
;         __builtin_amdgcn_global_load_lds((const unsigned*)((const char*)(gbase) + (voff)[_i]), (PG8_LAS unsigned*)(lds + (bufoff) + ldsw + _i * 8192), 16, 0, 0); } while (0)
; #define PG8_LDA(dst, b, h) do { _Pragma("unroll") for (int m = 0; m < 4; ++m) _Pragma("unroll") for (int k = 0; k < 2; ++k) dst[m][k] = *(const PG8_LAS bf16x8*)(lds + PG8_SA(b, h) + aoff + m * 2048 + k * 1024); } while (0)
; #define PG8_WAIT_V(n) asm volatile("s_waitcnt vmcnt(" #n ")" ::: "memory")
; template <class Epi, class Sched, bool ALIGN_EPI = false, bool SP2 = false>
; __device__ __forceinline__ void gemm_phase(PG8_LAS unsigned char* lds, const Gemm g, const Sched& S, const Epi& E) {
;     ...
;             PG8_LDA(At, 1, 1); PG8_STAGE(PG8_SB(1, 0), b3, voffB); PG8_STAGE(PG8_SB(1, 1), b3 + hstep, voffB); PG8_STAGE(PG8_SA(1, 0), a3, voffA);
;             PG8_WAIT_V(8); PG8_WAIT_L(0); PG8_BAR; PG8_MMA(1, 0, At, B0); PG8_MMA(1, 1, At, B1); PG8_BAR; PG8_SCHED;
;             } else {
;             PG8_LDB(B0, 0, 0); PG8_SCHED; PG8_LDA(At, 0, 0); PG8_STAGE(PG8_SA(1, 1), a1 + hstep, voffA);
;             PG8_WAIT_L(8); PG8_BAR; PG8_WAIT_L(0); PG8_MMA(0, 0, At, B0); PG8_BAR; PG8_SCHED;
;             PG8_LDB(B1, 0, 1); PG8_STAGE(PG8_SB(0, 0), b2, voffB);
;             PG8_BAR; PG8_WAIT_L(0); PG8_MMA(0, 1, At, B1); PG8_BAR;
;             PG8_LDA(At, 0, 1); PG8_STAGE(PG8_SA(0, 0), a2, voffA);
;             PG8_BAR; PG8_WAIT_L(0); PG8_MMA(1, 0, At, B0); PG8_BAR; PG8_SCHED;
;             PG8_STAGE(PG8_SB(0, 1), b2 + hstep, voffB);
;             PG8_WAIT_V(6); PG8_BAR; PG8_MMA(1, 1, At, B1); PG8_BAR;
;             PG8_LDB(B0, 1, 0); PG8_SCHED; PG8_LDA(At, 1, 0); PG8_STAGE(PG8_SA(0, 1), a2 + hstep, voffA);
;             PG8_WAIT_L(8); PG8_BAR; PG8_WAIT_L(0); PG8_MMA(0, 0, At, B0); PG8_BAR; PG8_SCHED;
;             PG8_LDB(B1, 1, 1); PG8_STAGE(PG8_SB(1, 0), b3, voffB);
;             PG8_BAR; PG8_WAIT_L(0); PG8_MMA(0, 1, At, B1); PG8_BAR;
;             PG8_LDA(At, 1, 1); PG8_STAGE(PG8_SA(1, 0), a3, voffA);
;             PG8_BAR; PG8_WAIT_L(0); PG8_MMA(1, 0, At, B0); PG8_BAR; PG8_SCHED;
;             PG8_STAGE(PG8_SB(1, 1), b3 + hstep, voffB);
;             PG8_WAIT_V(6); PG8_BAR; PG8_MMA(1, 1, At, B1); PG8_BAR;
;             }
;         }
;         if constexpr (ALIGN_EPI) { if (wr == 0) PG8_BAR; }
	s_add_i32 s18, s18, s27
	v_lshl_add_u64 v[194:195], v[194:195], 0, s[30:31]
	s_mov_b32 m0, s18
	ds_read_b128 v[178:181], v144 offset:49152
	ds_read_b128 v[182:185], v144 offset:50176
	ds_read_b128 v[186:189], v144 offset:51200
	ds_read_b128 v[190:193], v144 offset:52224
	ds_read_b128 v[202:205], v144 offset:53248
	ds_read_b128 v[206:209], v144 offset:54272
	ds_read_b128 v[210:213], v144 offset:55296
	ds_read_b128 v[214:217], v144 offset:56320
	global_load_lds_dwordx4 v[194:195], off
	s_add_i32 m0, s18, 0x2000
	s_add_u32 s38, s56, 0x40080
	v_lshl_add_u64 v[194:195], v[218:219], 0, s[30:31]
	s_addc_u32 s39, s57, 0
	s_add_i32 s18, s83, s27
	global_load_lds_dwordx4 v[194:195], off
	v_lshl_add_u64 v[194:195], s[38:39], 0, v[0:1]
	s_mov_b32 m0, s18
	s_nop 0
	global_load_lds_dwordx4 v[194:195], off
	v_lshl_add_u64 v[194:195], s[38:39], 0, v[130:131]
	s_add_i32 m0, s18, 0x2000
	s_nop 0
	global_load_lds_dwordx4 v[194:195], off
	v_lshl_add_u64 v[194:195], v[220:221], 0, s[30:31]
	s_mov_b32 m0, s71
	s_nop 0
	global_load_lds_dwordx4 v[194:195], off
	v_lshl_add_u64 v[194:195], v[222:223], 0, s[30:31]
	s_mov_b32 m0, s72
	s_nop 0
	global_load_lds_dwordx4 v[194:195], off
	s_waitcnt vmcnt(8)
	s_waitcnt lgkmcnt(0)
	s_barrier
	s_setprio 1
	s_waitcnt lgkmcnt(0)
	v_mfma_f32_16x16x32_bf16 v[50:53], v[146:149], v[178:181], v[50:53]
	v_mfma_f32_16x16x32_bf16 v[50:53], v[150:153], v[182:185], v[50:53]
	v_mfma_f32_16x16x32_bf16 v[34:37], v[146:149], v[186:189], v[34:37]
	v_mfma_f32_16x16x32_bf16 v[34:37], v[150:153], v[190:193], v[34:37]
	v_mfma_f32_16x16x32_bf16 v[18:21], v[146:149], v[202:205], v[18:21]
	v_mfma_f32_16x16x32_bf16 v[18:21], v[150:153], v[206:209], v[18:21]
	v_mfma_f32_16x16x32_bf16 v[2:5], v[146:149], v[210:213], v[2:5]
	v_mfma_f32_16x16x32_bf16 v[2:5], v[150:153], v[214:217], v[2:5]
	v_mfma_f32_16x16x32_bf16 v[54:57], v[154:157], v[178:181], v[54:57]
	v_mfma_f32_16x16x32_bf16 v[54:57], v[158:161], v[182:185], v[54:57]
	v_mfma_f32_16x16x32_bf16 v[38:41], v[154:157], v[186:189], v[38:41]
	v_mfma_f32_16x16x32_bf16 v[38:41], v[158:161], v[190:193], v[38:41]
	v_mfma_f32_16x16x32_bf16 v[22:25], v[154:157], v[202:205], v[22:25]
	v_mfma_f32_16x16x32_bf16 v[22:25], v[158:161], v[206:209], v[22:25]
	v_mfma_f32_16x16x32_bf16 v[6:9], v[154:157], v[210:213], v[6:9]
	v_mfma_f32_16x16x32_bf16 v[6:9], v[158:161], v[214:217], v[6:9]
	v_mfma_f32_16x16x32_bf16 v[58:61], v[162:165], v[178:181], v[58:61]
	v_mfma_f32_16x16x32_bf16 v[58:61], v[166:169], v[182:185], v[58:61]
	v_mfma_f32_16x16x32_bf16 v[42:45], v[162:165], v[186:189], v[42:45]
	v_mfma_f32_16x16x32_bf16 v[42:45], v[166:169], v[190:193], v[42:45]
	v_mfma_f32_16x16x32_bf16 v[26:29], v[162:165], v[202:205], v[26:29]
	v_mfma_f32_16x16x32_bf16 v[26:29], v[166:169], v[206:209], v[26:29]
	v_mfma_f32_16x16x32_bf16 v[10:13], v[162:165], v[210:213], v[10:13]
	v_mfma_f32_16x16x32_bf16 v[10:13], v[166:169], v[214:217], v[10:13]
	v_mfma_f32_16x16x32_bf16 v[62:65], v[170:173], v[178:181], v[62:65]
	v_mfma_f32_16x16x32_bf16 v[62:65], v[174:177], v[182:185], v[62:65]
	v_mfma_f32_16x16x32_bf16 v[46:49], v[170:173], v[186:189], v[46:49]
	v_mfma_f32_16x16x32_bf16 v[46:49], v[174:177], v[190:193], v[46:49]
	v_mfma_f32_16x16x32_bf16 v[30:33], v[170:173], v[202:205], v[30:33]
	v_mfma_f32_16x16x32_bf16 v[30:33], v[174:177], v[206:209], v[30:33]
	v_mfma_f32_16x16x32_bf16 v[14:17], v[170:173], v[210:213], v[14:17]
	v_mfma_f32_16x16x32_bf16 v[14:17], v[174:177], v[214:217], v[14:17]
	s_setprio 0
	s_barrier
	s_add_i32 s82, s82, 2
	s_add_u32 s60, s60, 0x100
	s_addc_u32 s61, s61, 0
	s_add_u32 s80, s80, 0x100
	s_addc_u32 s81, s81, 0
	s_cmp_gt_u32 s82, 13
	s_cbranch_scc0 .LBB0_220
	s_and_b64 vcc, exec, s[44:45]
	s_cbranch_vccz .LBB0_223
	s_barrier

; #define PG8_STAGE(bufoff, gbase, voff) do { _Pragma("unroll") for (int _i = 0; _i < 2; ++_i) \
;         __builtin_amdgcn_global_load_lds((const unsigned*)((const char*)(gbase) + (voff)[_i]), (PG8_LAS unsigned*)(lds + (bufoff) + ldsw + _i * 8192), 16, 0, 0); } while (0)
; #define PG8_LDA(dst, b, h) do { _Pragma("unroll") for (int m = 0; m < 4; ++m) _Pragma("unroll") for (int k = 0; k < 2; ++k) dst[m][k] = *(const PG8_LAS bf16x8*)(lds + PG8_SA(b, h) + aoff + m * 2048 + k * 1024); } while (0)
; #define PG8_LDB(dst, b, h) do { _Pragma("unroll") for (int n = 0; n < 2; ++n) _Pragma("unroll") for (int k = 0; k < 2; ++k) dst[n][k] = *(const PG8_LAS bf16x8*)(lds + PG8_SB(b, h) + boff + n * 2048 + k * 1024); } while (0)
; #define PG8_WAIT_V(n) asm volatile("s_waitcnt vmcnt(" #n ")" ::: "memory")
; #define PG8_WAIT_L(n) asm volatile("s_waitcnt lgkmcnt(" #n ")" ::: "memory")
; #define PG8_BAR __builtin_amdgcn_s_barrier()
; #define PG8_SCHED __builtin_amdgcn_sched_barrier(0)
; template <class Epi, class Sched, bool ALIGN_EPI = false, bool SP2 = false>
; __device__ __forceinline__ void gemm_phase(PG8_LAS unsigned char* lds, const Gemm g, const Sched& S, const Epi& E) {
;     ...
;         const bool has_next = S.next(ui + 1, nxt);
;         const char* nA = has_next ? (const char*)g.A + (size_t)nxt.pm * tstep : cA; const char* nB = has_next ? (const char*)g.Bt + (size_t)nxt.pn * tstep : cB;
;         for (int t = 0; t < nt; t += 2) {
;             const bool last = (t == nt - 2);
;             const char* a1 = cA + (size_t)(t + 1) * kstep;
;             const char* a2 = last ? nA : cA + (size_t)(t + 2) * kstep; const char* b2 = last ? nB : cB + (size_t)(t + 2) * kstep;
;             const char* a3 = a2 + kstep; const char* b3 = b2 + kstep;
;             if (last && has_next) S.a_ready(nxt);
;             if constexpr (SP2) {
;             PG8_LDB(B0, 0, 0); PG8_LDB(B1, 0, 1); PG8_SCHED; PG8_LDA(At, 0, 0); PG8_STAGE(PG8_SA(1, 1), a1 + hstep, voffA);
;             PG8_WAIT_V(8); PG8_WAIT_L(0); PG8_BAR; PG8_MMA(0, 0, At, B0); PG8_MMA(0, 1, At, B1); PG8_BAR; PG8_SCHED;
;             PG8_LDA(At, 0, 1); PG8_STAGE(PG8_SB(0, 0), b2, voffB); PG8_STAGE(PG8_SB(0, 1), b2 + hstep, voffB); PG8_STAGE(PG8_SA(0, 0), a2, voffA);
;             PG8_WAIT_V(8); PG8_WAIT_L(0); PG8_BAR; PG8_MMA(1, 0, At, B0); PG8_MMA(1, 1, At, B1); PG8_BAR; PG8_SCHED;
.LBB0_274:
	s_add_i32 vcc_lo, s46, 2
	s_add_u32 s38, s48, 0x80
	s_addc_u32 s39, s49, 0
	s_add_i32 vcc_hi, 0, 0x10000
	s_cmp_eq_u32 s99, s46
	s_cselect_b32 s47, s81, s39
	s_cselect_b32 s46, s80, s38
	s_cselect_b32 s39, s83, s51
	s_cselect_b32 s38, s82, s50
	s_add_i32 s18, 0, 0x14000
	v_add_u32_e32 v142, vcc_hi, v245
	v_add_u32_e32 v158, s18, v245
	ds_read_b128 v[110:113], v142
	ds_read_b128 v[118:121], v142 offset:1024
	ds_read_b128 v[138:141], v142 offset:2048
	ds_read_b128 v[142:145], v142 offset:3072
	ds_read_b128 v[146:149], v158
	ds_read_b128 v[150:153], v158 offset:1024
	ds_read_b128 v[154:157], v158 offset:2048
	ds_read_b128 v[158:161], v158 offset:3072
	v_lshl_add_u64 v[210:211], s[48:49], 0, v[206:207]
	s_add_i32 m0, s92, 0xc000
	ds_read_b128 v[162:165], v247
	ds_read_b128 v[166:169], v247 offset:1024
	ds_read_b128 v[170:173], v247 offset:2048
	ds_read_b128 v[174:177], v247 offset:3072
	ds_read_b128 v[178:181], v247 offset:4096
	ds_read_b128 v[182:185], v247 offset:5120
	ds_read_b128 v[186:189], v247 offset:6144
	ds_read_b128 v[190:193], v247 offset:7168
	global_load_lds_dwordx4 v[210:211], off
	v_lshl_add_u64 v[210:211], s[48:49], 0, v[208:209]
	s_add_i32 m0, s92, 0xe000
	s_nop 0
	global_load_lds_dwordx4 v[210:211], off
	s_waitcnt vmcnt(8)
	s_waitcnt lgkmcnt(0)
	s_barrier
	s_setprio 1
	s_waitcnt lgkmcnt(0)
	v_mfma_f32_16x16x32_bf16 v[130:133], v[110:113], v[162:165], v[130:133]
	v_mfma_f32_16x16x32_bf16 v[130:133], v[118:121], v[166:169], v[130:133]
	v_mfma_f32_16x16x32_bf16 v[114:117], v[110:113], v[170:173], v[114:117]
	v_mfma_f32_16x16x32_bf16 v[114:117], v[118:121], v[174:177], v[114:117]
	v_mfma_f32_16x16x32_bf16 v[94:97], v[110:113], v[178:181], v[94:97]
	v_mfma_f32_16x16x32_bf16 v[94:97], v[118:121], v[182:185], v[94:97]
	v_mfma_f32_16x16x32_bf16 v[78:81], v[110:113], v[186:189], v[78:81]
	v_mfma_f32_16x16x32_bf16 v[78:81], v[118:121], v[190:193], v[78:81]
	v_mfma_f32_16x16x32_bf16 v[134:137], v[138:141], v[162:165], v[134:137]
	v_mfma_f32_16x16x32_bf16 v[134:137], v[142:145], v[166:169], v[134:137]
	v_mfma_f32_16x16x32_bf16 v[106:109], v[138:141], v[170:173], v[106:109]
	v_mfma_f32_16x16x32_bf16 v[106:109], v[142:145], v[174:177], v[106:109]
	v_mfma_f32_16x16x32_bf16 v[90:93], v[138:141], v[178:181], v[90:93]
	v_mfma_f32_16x16x32_bf16 v[90:93], v[142:145], v[182:185], v[90:93]
	v_mfma_f32_16x16x32_bf16 v[74:77], v[138:141], v[186:189], v[74:77]
	v_mfma_f32_16x16x32_bf16 v[74:77], v[142:145], v[190:193], v[74:77]
	v_mfma_f32_16x16x32_bf16 v[126:129], v[146:149], v[162:165], v[126:129]
	v_mfma_f32_16x16x32_bf16 v[126:129], v[150:153], v[166:169], v[126:129]
	v_mfma_f32_16x16x32_bf16 v[102:105], v[146:149], v[170:173], v[102:105]
	v_mfma_f32_16x16x32_bf16 v[102:105], v[150:153], v[174:177], v[102:105]
	v_mfma_f32_16x16x32_bf16 v[86:89], v[146:149], v[178:181], v[86:89]
	v_mfma_f32_16x16x32_bf16 v[86:89], v[150:153], v[182:185], v[86:89]
	v_mfma_f32_16x16x32_bf16 v[70:73], v[146:149], v[186:189], v[70:73]
	v_mfma_f32_16x16x32_bf16 v[70:73], v[150:153], v[190:193], v[70:73]
	v_mfma_f32_16x16x32_bf16 v[122:125], v[154:157], v[162:165], v[122:125]
	v_mfma_f32_16x16x32_bf16 v[122:125], v[158:161], v[166:169], v[122:125]
	v_mfma_f32_16x16x32_bf16 v[98:101], v[154:157], v[170:173], v[98:101]
	v_mfma_f32_16x16x32_bf16 v[98:101], v[158:161], v[174:177], v[98:101]
	v_mfma_f32_16x16x32_bf16 v[82:85], v[154:157], v[178:181], v[82:85]
	v_mfma_f32_16x16x32_bf16 v[82:85], v[158:161], v[182:185], v[82:85]
	v_mfma_f32_16x16x32_bf16 v[66:69], v[154:157], v[186:189], v[66:69]
	v_mfma_f32_16x16x32_bf16 v[66:69], v[158:161], v[190:193], v[66:69]
	s_setprio 0
	s_barrier
	s_add_i32 vcc_hi, vcc_hi, s6
	v_lshl_add_u64 v[210:211], s[38:39], 0, v[0:1]
	s_mov_b32 m0, vcc_hi
	ds_read_b128 v[162:165], v247 offset:16384
	ds_read_b128 v[166:169], v247 offset:17408
	ds_read_b128 v[170:173], v247 offset:18432
	ds_read_b128 v[174:177], v247 offset:19456
	ds_read_b128 v[178:181], v247 offset:20480
	ds_read_b128 v[182:185], v247 offset:21504
	ds_read_b128 v[186:189], v247 offset:22528
	ds_read_b128 v[190:193], v247 offset:23552
	global_load_lds_dwordx4 v[210:211], off
	s_add_i32 m0, vcc_hi, 0x2000
	v_lshl_add_u64 v[212:213], s[38:39], 0, v[204:205]
	s_add_u32 s38, s38, s58
	s_addc_u32 s39, s39, 0
	s_add_i32 s18, s18, s6
	global_load_lds_dwordx4 v[212:213], off
	v_lshl_add_u64 v[214:215], s[38:39], 0, v[0:1]
	s_mov_b32 m0, s18
	v_lshl_add_u64 v[216:217], s[38:39], 0, v[204:205]
	global_load_lds_dwordx4 v[214:215], off
	s_add_i32 m0, s18, 0x2000
	v_lshl_add_u64 v[218:219], s[46:47], 0, v[194:195]
	global_load_lds_dwordx4 v[216:217], off
	s_mov_b32 m0, s92
	v_lshl_add_u64 v[220:221], s[46:47], 0, v[202:203]
	global_load_lds_dwordx4 v[218:219], off
	s_mov_b32 m0, s93
	s_nop 0
	global_load_lds_dwordx4 v[220:221], off
	s_waitcnt vmcnt(8)
	s_waitcnt lgkmcnt(0)
	s_barrier
; #define PG8_STAGE(bufoff, gbase, voff) do { _Pragma("unroll") for (int _i = 0; _i < 2; ++_i) \
;         __builtin_amdgcn_global_load_lds((const unsigned*)((const char*)(gbase) + (voff)[_i]), (PG8_LAS unsigned*)(lds + (bufoff) + ldsw + _i * 8192), 16, 0, 0); } while (0)
; #define PG8_LDA(dst, b, h) do { _Pragma("unroll") for (int m = 0; m < 4; ++m) _Pragma("unroll") for (int k = 0; k < 2; ++k) dst[m][k] = *(const PG8_LAS bf16x8*)(lds + PG8_SA(b, h) + aoff + m * 2048 + k * 1024); } while (0)
; #define PG8_LDB(dst, b, h) do { _Pragma("unroll") for (int n = 0; n < 2; ++n) _Pragma("unroll") for (int k = 0; k < 2; ++k) dst[n][k] = *(const PG8_LAS bf16x8*)(lds + PG8_SB(b, h) + boff + n * 2048 + k * 1024); } while (0)
; #define PG8_MMA(ai, bj, At, Bt) do { __builtin_amdgcn_s_setprio(1); _Pragma("unroll") for (int m = 0; m < 4; ++m) _Pragma("unroll") for (int n = 0; n < 2; ++n) _Pragma("unroll") for (int k = 0; k < 2; ++k) \
;         acc[ai][bj][m][n] = __builtin_amdgcn_mfma_f32_16x16x32_bf16(Bt[n][k], At[m][k], acc[ai][bj][m][n], 0, 0, 0); __builtin_amdgcn_s_setprio(0); } while (0)
; #define PG8_WAIT_V(n) asm volatile("s_waitcnt vmcnt(" #n ")" ::: "memory")
; #define PG8_WAIT_L(n) asm volatile("s_waitcnt lgkmcnt(" #n ")" ::: "memory")
; #define PG8_BAR __builtin_amdgcn_s_barrier()
; #define PG8_SCHED __builtin_amdgcn_sched_barrier(0)
; template <class Epi, class Sched, bool ALIGN_EPI = false, bool SP2 = false>
; __device__ __forceinline__ void gemm_phase(PG8_LAS unsigned char* lds, const Gemm g, const Sched& S, const Epi& E) {
;     ...
;             PG8_WAIT_V(8); PG8_WAIT_L(0); PG8_BAR; PG8_MMA(1, 0, At, B0); PG8_MMA(1, 1, At, B1); PG8_BAR; PG8_SCHED;
;             PG8_LDB(B0, 1, 0); PG8_LDB(B1, 1, 1); PG8_SCHED; PG8_LDA(At, 1, 0); PG8_STAGE(PG8_SA(0, 1), a2 + hstep, voffA);
;             PG8_WAIT_V(8); PG8_WAIT_L(0); PG8_BAR; PG8_MMA(0, 0, At, B0); PG8_MMA(0, 1, At, B1); PG8_BAR; PG8_SCHED;
	s_setprio 1
	s_waitcnt lgkmcnt(0)
	v_mfma_f32_16x16x32_bf16 v[62:65], v[110:113], v[162:165], v[62:65]
	v_mfma_f32_16x16x32_bf16 v[62:65], v[118:121], v[166:169], v[62:65]
	v_mfma_f32_16x16x32_bf16 v[46:49], v[110:113], v[170:173], v[46:49]
	v_mfma_f32_16x16x32_bf16 v[46:49], v[118:121], v[174:177], v[46:49]
	v_mfma_f32_16x16x32_bf16 v[30:33], v[110:113], v[178:181], v[30:33]
	v_mfma_f32_16x16x32_bf16 v[30:33], v[118:121], v[182:185], v[30:33]
	v_mfma_f32_16x16x32_bf16 v[14:17], v[110:113], v[186:189], v[14:17]
	v_mfma_f32_16x16x32_bf16 v[14:17], v[118:121], v[190:193], v[14:17]
	v_mfma_f32_16x16x32_bf16 v[58:61], v[138:141], v[162:165], v[58:61]
	v_mfma_f32_16x16x32_bf16 v[58:61], v[142:145], v[166:169], v[58:61]
	v_mfma_f32_16x16x32_bf16 v[42:45], v[138:141], v[170:173], v[42:45]
	v_mfma_f32_16x16x32_bf16 v[42:45], v[142:145], v[174:177], v[42:45]
	v_mfma_f32_16x16x32_bf16 v[26:29], v[138:141], v[178:181], v[26:29]
	v_mfma_f32_16x16x32_bf16 v[26:29], v[142:145], v[182:185], v[26:29]
	v_mfma_f32_16x16x32_bf16 v[10:13], v[138:141], v[186:189], v[10:13]
	v_mfma_f32_16x16x32_bf16 v[10:13], v[142:145], v[190:193], v[10:13]
	v_mfma_f32_16x16x32_bf16 v[54:57], v[146:149], v[162:165], v[54:57]
	v_mfma_f32_16x16x32_bf16 v[54:57], v[150:153], v[166:169], v[54:57]
	v_mfma_f32_16x16x32_bf16 v[38:41], v[146:149], v[170:173], v[38:41]
	v_mfma_f32_16x16x32_bf16 v[38:41], v[150:153], v[174:177], v[38:41]
	v_mfma_f32_16x16x32_bf16 v[22:25], v[146:149], v[178:181], v[22:25]
	v_mfma_f32_16x16x32_bf16 v[22:25], v[150:153], v[182:185], v[22:25]
	v_mfma_f32_16x16x32_bf16 v[6:9], v[146:149], v[186:189], v[6:9]
	v_mfma_f32_16x16x32_bf16 v[6:9], v[150:153], v[190:193], v[6:9]
	v_mfma_f32_16x16x32_bf16 v[50:53], v[154:157], v[162:165], v[50:53]
	v_mfma_f32_16x16x32_bf16 v[50:53], v[158:161], v[166:169], v[50:53]
	v_mfma_f32_16x16x32_bf16 v[34:37], v[154:157], v[170:173], v[34:37]
	v_mfma_f32_16x16x32_bf16 v[34:37], v[158:161], v[174:177], v[34:37]
	v_mfma_f32_16x16x32_bf16 v[18:21], v[154:157], v[178:181], v[18:21]
	v_mfma_f32_16x16x32_bf16 v[18:21], v[158:161], v[182:185], v[18:21]
	v_mfma_f32_16x16x32_bf16 v[2:5], v[154:157], v[186:189], v[2:5]
	v_mfma_f32_16x16x32_bf16 v[2:5], v[158:161], v[190:193], v[2:5]
	s_setprio 0
	s_barrier
	s_add_i32 s18, 0, 0x18000
	s_add_i32 vcc_hi, 0, 0x1c000
	v_add_u32_e32 v142, s18, v245
	v_add_u32_e32 v158, vcc_hi, v245
	ds_read_b128 v[110:113], v142
	ds_read_b128 v[118:121], v142 offset:1024
	ds_read_b128 v[138:141], v142 offset:2048
	ds_read_b128 v[142:145], v142 offset:3072
	ds_read_b128 v[146:149], v158
	ds_read_b128 v[150:153], v158 offset:1024
	ds_read_b128 v[154:157], v158 offset:2048
	ds_read_b128 v[158:161], v158 offset:3072
	s_add_u32 s38, s46, s58
	s_addc_u32 s39, s47, 0
	s_mov_b32 m0, s94
	v_lshl_add_u64 v[222:223], s[38:39], 0, v[194:195]
	ds_read_b128 v[162:165], v247 offset:32768
	ds_read_b128 v[166:169], v247 offset:33792
	ds_read_b128 v[170:173], v247 offset:34816
	ds_read_b128 v[174:177], v247 offset:35840
	ds_read_b128 v[178:181], v247 offset:36864
	ds_read_b128 v[182:185], v247 offset:37888
	ds_read_b128 v[186:189], v247 offset:38912
	ds_read_b128 v[190:193], v247 offset:39936
	global_load_lds_dwordx4 v[222:223], off
	v_lshl_add_u64 v[222:223], s[38:39], 0, v[202:203]
	s_mov_b32 m0, s95
	s_nop 0
	global_load_lds_dwordx4 v[222:223], off
	s_waitcnt vmcnt(8)
	s_waitcnt lgkmcnt(0)
	s_barrier
	s_setprio 1
	s_waitcnt lgkmcnt(0)
	v_mfma_f32_16x16x32_bf16 v[130:133], v[110:113], v[162:165], v[130:133]
	v_mfma_f32_16x16x32_bf16 v[130:133], v[118:121], v[166:169], v[130:133]
	v_mfma_f32_16x16x32_bf16 v[114:117], v[110:113], v[170:173], v[114:117]
	v_mfma_f32_16x16x32_bf16 v[114:117], v[118:121], v[174:177], v[114:117]
	v_mfma_f32_16x16x32_bf16 v[94:97], v[110:113], v[178:181], v[94:97]
	v_mfma_f32_16x16x32_bf16 v[94:97], v[118:121], v[182:185], v[94:97]
	v_mfma_f32_16x16x32_bf16 v[78:81], v[110:113], v[186:189], v[78:81]
	v_mfma_f32_16x16x32_bf16 v[78:81], v[118:121], v[190:193], v[78:81]
	v_mfma_f32_16x16x32_bf16 v[134:137], v[138:141], v[162:165], v[134:137]
	v_mfma_f32_16x16x32_bf16 v[134:137], v[142:145], v[166:169], v[134:137]
	v_mfma_f32_16x16x32_bf16 v[106:109], v[138:141], v[170:173], v[106:109]
	v_mfma_f32_16x16x32_bf16 v[106:109], v[142:145], v[174:177], v[106:109]
	v_mfma_f32_16x16x32_bf16 v[90:93], v[138:141], v[178:181], v[90:93]
	v_mfma_f32_16x16x32_bf16 v[90:93], v[142:145], v[182:185], v[90:93]
	v_mfma_f32_16x16x32_bf16 v[74:77], v[138:141], v[186:189], v[74:77]
	v_mfma_f32_16x16x32_bf16 v[74:77], v[142:145], v[190:193], v[74:77]
	v_mfma_f32_16x16x32_bf16 v[126:129], v[146:149], v[162:165], v[126:129]
	v_mfma_f32_16x16x32_bf16 v[126:129], v[150:153], v[166:169], v[126:129]
	v_mfma_f32_16x16x32_bf16 v[102:105], v[146:149], v[170:173], v[102:105]
	v_mfma_f32_16x16x32_bf16 v[102:105], v[150:153], v[174:177], v[102:105]
	v_mfma_f32_16x16x32_bf16 v[86:89], v[146:149], v[178:181], v[86:89]
	v_mfma_f32_16x16x32_bf16 v[86:89], v[150:153], v[182:185], v[86:89]
	v_mfma_f32_16x16x32_bf16 v[70:73], v[146:149], v[186:189], v[70:73]
	v_mfma_f32_16x16x32_bf16 v[70:73], v[150:153], v[190:193], v[70:73]
	v_mfma_f32_16x16x32_bf16 v[122:125], v[154:157], v[162:165], v[122:125]
	v_mfma_f32_16x16x32_bf16 v[122:125], v[158:161], v[166:169], v[122:125]
	v_mfma_f32_16x16x32_bf16 v[98:101], v[154:157], v[170:173], v[98:101]
	v_mfma_f32_16x16x32_bf16 v[98:101], v[158:161], v[174:177], v[98:101]
	v_mfma_f32_16x16x32_bf16 v[82:85], v[154:157], v[178:181], v[82:85]
	v_mfma_f32_16x16x32_bf16 v[82:85], v[158:161], v[182:185], v[82:85]
	v_mfma_f32_16x16x32_bf16 v[66:69], v[154:157], v[186:189], v[66:69]
	v_mfma_f32_16x16x32_bf16 v[66:69], v[158:161], v[190:193], v[66:69]
	s_setprio 0
	s_barrier
; #define PG8_STAGE(bufoff, gbase, voff) do { _Pragma("unroll") for (int _i = 0; _i < 2; ++_i) \
;         __builtin_amdgcn_global_load_lds((const unsigned*)((const char*)(gbase) + (voff)[_i]), (PG8_LAS unsigned*)(lds + (bufoff) + ldsw + _i * 8192), 16, 0, 0); } while (0)
; #define PG8_LDA(dst, b, h) do { _Pragma("unroll") for (int m = 0; m < 4; ++m) _Pragma("unroll") for (int k = 0; k < 2; ++k) dst[m][k] = *(const PG8_LAS bf16x8*)(lds + PG8_SA(b, h) + aoff + m * 2048 + k * 1024); } while (0)
; #define PG8_WAIT_V(n) asm volatile("s_waitcnt vmcnt(" #n ")" ::: "memory")
; template <class Epi, class Sched, bool ALIGN_EPI = false, bool SP2 = false>
; __device__ __forceinline__ void gemm_phase(PG8_LAS unsigned char* lds, const Gemm g, const Sched& S, const Epi& E) {
;     ...
;             PG8_LDA(At, 1, 1); PG8_STAGE(PG8_SB(1, 0), b3, voffB); PG8_STAGE(PG8_SB(1, 1), b3 + hstep, voffB); PG8_STAGE(PG8_SA(1, 0), a3, voffA);
;             PG8_WAIT_V(8); PG8_WAIT_L(0); PG8_BAR; PG8_MMA(1, 0, At, B0); PG8_MMA(1, 1, At, B1); PG8_BAR; PG8_SCHED;
;             } else {
;             PG8_LDB(B0, 0, 0); PG8_SCHED; PG8_LDA(At, 0, 0); PG8_STAGE(PG8_SA(1, 1), a1 + hstep, voffA);
;             PG8_WAIT_L(8); PG8_BAR; PG8_WAIT_L(0); PG8_MMA(0, 0, At, B0); PG8_BAR; PG8_SCHED;
;             PG8_LDB(B1, 0, 1); PG8_STAGE(PG8_SB(0, 0), b2, voffB);
;             PG8_BAR; PG8_WAIT_L(0); PG8_MMA(0, 1, At, B1); PG8_BAR;
;             PG8_LDA(At, 0, 1); PG8_STAGE(PG8_SA(0, 0), a2, voffA);
;             PG8_BAR; PG8_WAIT_L(0); PG8_MMA(1, 0, At, B0); PG8_BAR; PG8_SCHED;
;             PG8_STAGE(PG8_SB(0, 1), b2 + hstep, voffB);
;             PG8_WAIT_V(6); PG8_BAR; PG8_MMA(1, 1, At, B1); PG8_BAR;
;             PG8_LDB(B0, 1, 0); PG8_SCHED; PG8_LDA(At, 1, 0); PG8_STAGE(PG8_SA(0, 1), a2 + hstep, voffA);
;             PG8_WAIT_L(8); PG8_BAR; PG8_WAIT_L(0); PG8_MMA(0, 0, At, B0); PG8_BAR; PG8_SCHED;
;             PG8_LDB(B1, 1, 1); PG8_STAGE(PG8_SB(1, 0), b3, voffB);
;             PG8_BAR; PG8_WAIT_L(0); PG8_MMA(0, 1, At, B1); PG8_BAR;
;             PG8_LDA(At, 1, 1); PG8_STAGE(PG8_SA(1, 0), a3, voffA);
;             PG8_BAR; PG8_WAIT_L(0); PG8_MMA(1, 0, At, B0); PG8_BAR; PG8_SCHED;
;             PG8_STAGE(PG8_SB(1, 1), b3 + hstep, voffB);
;             PG8_WAIT_V(6); PG8_BAR; PG8_MMA(1, 1, At, B1); PG8_BAR;
;             }
;         }
;         if constexpr (ALIGN_EPI) { if (wr == 0) PG8_BAR; }
	s_add_i32 s18, s18, s6
	v_lshl_add_u64 v[210:211], v[210:211], 0, s[30:31]
	s_mov_b32 m0, s18
	ds_read_b128 v[162:165], v247 offset:49152
	ds_read_b128 v[166:169], v247 offset:50176
	ds_read_b128 v[170:173], v247 offset:51200
	ds_read_b128 v[174:177], v247 offset:52224
	ds_read_b128 v[178:181], v247 offset:53248
	ds_read_b128 v[182:185], v247 offset:54272
	ds_read_b128 v[186:189], v247 offset:55296
	ds_read_b128 v[190:193], v247 offset:56320
	global_load_lds_dwordx4 v[210:211], off
	v_lshl_add_u64 v[210:211], v[212:213], 0, s[30:31]
	s_add_i32 m0, s18, 0x2000
	s_add_i32 s18, vcc_hi, s6
	global_load_lds_dwordx4 v[210:211], off
	v_lshl_add_u64 v[210:211], v[214:215], 0, s[30:31]
	s_mov_b32 m0, s18
	s_nop 0
	global_load_lds_dwordx4 v[210:211], off
	v_lshl_add_u64 v[210:211], v[216:217], 0, s[30:31]
	s_add_i32 m0, s18, 0x2000
	s_nop 0
	global_load_lds_dwordx4 v[210:211], off
	v_lshl_add_u64 v[210:211], v[218:219], 0, s[30:31]
	s_mov_b32 m0, s97
	s_nop 0
	global_load_lds_dwordx4 v[210:211], off
	v_lshl_add_u64 v[210:211], v[220:221], 0, s[30:31]
	s_mov_b32 m0, s98
	s_nop 0
	global_load_lds_dwordx4 v[210:211], off
	s_waitcnt vmcnt(8)
	s_waitcnt lgkmcnt(0)
	s_barrier
	s_setprio 1
	s_waitcnt lgkmcnt(0)
	v_mfma_f32_16x16x32_bf16 v[62:65], v[110:113], v[162:165], v[62:65]
	v_mfma_f32_16x16x32_bf16 v[62:65], v[118:121], v[166:169], v[62:65]
	v_mfma_f32_16x16x32_bf16 v[46:49], v[110:113], v[170:173], v[46:49]
	v_mfma_f32_16x16x32_bf16 v[46:49], v[118:121], v[174:177], v[46:49]
	v_mfma_f32_16x16x32_bf16 v[30:33], v[110:113], v[178:181], v[30:33]
	v_mfma_f32_16x16x32_bf16 v[30:33], v[118:121], v[182:185], v[30:33]
	v_mfma_f32_16x16x32_bf16 v[14:17], v[110:113], v[186:189], v[14:17]
	v_mfma_f32_16x16x32_bf16 v[14:17], v[118:121], v[190:193], v[14:17]
	v_mfma_f32_16x16x32_bf16 v[58:61], v[138:141], v[162:165], v[58:61]
	v_mfma_f32_16x16x32_bf16 v[58:61], v[142:145], v[166:169], v[58:61]
	v_mfma_f32_16x16x32_bf16 v[42:45], v[138:141], v[170:173], v[42:45]
	v_mfma_f32_16x16x32_bf16 v[42:45], v[142:145], v[174:177], v[42:45]
	v_mfma_f32_16x16x32_bf16 v[26:29], v[138:141], v[178:181], v[26:29]
	v_mfma_f32_16x16x32_bf16 v[26:29], v[142:145], v[182:185], v[26:29]
	v_mfma_f32_16x16x32_bf16 v[10:13], v[138:141], v[186:189], v[10:13]
	v_mfma_f32_16x16x32_bf16 v[10:13], v[142:145], v[190:193], v[10:13]
	v_mfma_f32_16x16x32_bf16 v[54:57], v[146:149], v[162:165], v[54:57]
	v_mfma_f32_16x16x32_bf16 v[54:57], v[150:153], v[166:169], v[54:57]
	v_mfma_f32_16x16x32_bf16 v[38:41], v[146:149], v[170:173], v[38:41]
	v_mfma_f32_16x16x32_bf16 v[38:41], v[150:153], v[174:177], v[38:41]
	v_mfma_f32_16x16x32_bf16 v[22:25], v[146:149], v[178:181], v[22:25]
	v_mfma_f32_16x16x32_bf16 v[22:25], v[150:153], v[182:185], v[22:25]
	v_mfma_f32_16x16x32_bf16 v[6:9], v[146:149], v[186:189], v[6:9]
	v_mfma_f32_16x16x32_bf16 v[6:9], v[150:153], v[190:193], v[6:9]
	v_mfma_f32_16x16x32_bf16 v[50:53], v[154:157], v[162:165], v[50:53]
	v_mfma_f32_16x16x32_bf16 v[50:53], v[158:161], v[166:169], v[50:53]
	v_mfma_f32_16x16x32_bf16 v[34:37], v[154:157], v[170:173], v[34:37]
	v_mfma_f32_16x16x32_bf16 v[34:37], v[158:161], v[174:177], v[34:37]
	v_mfma_f32_16x16x32_bf16 v[18:21], v[154:157], v[178:181], v[18:21]
	v_mfma_f32_16x16x32_bf16 v[18:21], v[158:161], v[182:185], v[18:21]
	v_mfma_f32_16x16x32_bf16 v[2:5], v[154:157], v[186:189], v[2:5]
	v_mfma_f32_16x16x32_bf16 v[2:5], v[158:161], v[190:193], v[2:5]
	s_setprio 0
	s_barrier
	s_add_u32 s48, s48, 0x100
	s_addc_u32 s49, s49, 0
	s_add_u32 s50, s50, 0x100
	s_addc_u32 s51, s51, 0
	s_cmp_ge_u32 vcc_lo, s96
	s_mov_b32 s46, vcc_lo
	s_cbranch_scc0 .LBB0_274
	s_and_b64 vcc, exec, s[72:73]
	s_cbranch_vccz .LBB0_277
	s_barrier

; #define PG8_STAGE(bufoff, gbase, voff) do { _Pragma("unroll") for (int _i = 0; _i < 2; ++_i) \
;         __builtin_amdgcn_global_load_lds((const unsigned*)((const char*)(gbase) + (voff)[_i]), (PG8_LAS unsigned*)(lds + (bufoff) + ldsw + _i * 8192), 16, 0, 0); } while (0)
; #define PG8_LDA(dst, b, h) do { _Pragma("unroll") for (int m = 0; m < 4; ++m) _Pragma("unroll") for (int k = 0; k < 2; ++k) dst[m][k] = *(const PG8_LAS bf16x8*)(lds + PG8_SA(b, h) + aoff + m * 2048 + k * 1024); } while (0)
; #define PG8_LDB(dst, b, h) do { _Pragma("unroll") for (int n = 0; n < 2; ++n) _Pragma("unroll") for (int k = 0; k < 2; ++k) dst[n][k] = *(const PG8_LAS bf16x8*)(lds + PG8_SB(b, h) + boff + n * 2048 + k * 1024); } while (0)
; #define PG8_WAIT_V(n) asm volatile("s_waitcnt vmcnt(" #n ")" ::: "memory")
; #define PG8_WAIT_L(n) asm volatile("s_waitcnt lgkmcnt(" #n ")" ::: "memory")
; #define PG8_BAR __builtin_amdgcn_s_barrier()
; #define PG8_SCHED __builtin_amdgcn_sched_barrier(0)
; template <class Epi, class Sched, bool ALIGN_EPI = false, bool SP2 = false>
; __device__ __forceinline__ void gemm_phase(PG8_LAS unsigned char* lds, const Gemm g, const Sched& S, const Epi& E) {
;     ...
;         const bool has_next = S.next(ui + 1, nxt);
;         const char* nA = has_next ? (const char*)g.A + (size_t)nxt.pm * tstep : cA; const char* nB = has_next ? (const char*)g.Bt + (size_t)nxt.pn * tstep : cB;
;         for (int t = 0; t < nt; t += 2) {
;             const bool last = (t == nt - 2);
;             const char* a1 = cA + (size_t)(t + 1) * kstep;
;             const char* a2 = last ? nA : cA + (size_t)(t + 2) * kstep; const char* b2 = last ? nB : cB + (size_t)(t + 2) * kstep;
;             const char* a3 = a2 + kstep; const char* b3 = b2 + kstep;
;             if (last && has_next) S.a_ready(nxt);
;             if constexpr (SP2) {
;             PG8_LDB(B0, 0, 0); PG8_LDB(B1, 0, 1); PG8_SCHED; PG8_LDA(At, 0, 0); PG8_STAGE(PG8_SA(1, 1), a1 + hstep, voffA);
;             PG8_WAIT_V(8); PG8_WAIT_L(0); PG8_BAR; PG8_MMA(0, 0, At, B0); PG8_MMA(0, 1, At, B1); PG8_BAR; PG8_SCHED;
;             PG8_LDA(At, 0, 1); PG8_STAGE(PG8_SB(0, 0), b2, voffB); PG8_STAGE(PG8_SB(0, 1), b2 + hstep, voffB); PG8_STAGE(PG8_SA(0, 0), a2, voffA);
;             PG8_WAIT_V(8); PG8_WAIT_L(0); PG8_BAR; PG8_MMA(1, 0, At, B0); PG8_MMA(1, 1, At, B1); PG8_BAR; PG8_SCHED;
.LBB0_408:
	s_add_u32 s38, s48, 0xfffc0080
	s_addc_u32 s39, s49, -1
	s_add_i32 s85, 0, 0x10000
	s_cmp_eq_u32 s84, 12
	s_cselect_b32 s73, s21, s39
	s_cselect_b32 s72, s27, s38
	v_add_u32_e32 v0, s85, v167
	s_cselect_b32 s47, s29, s69
	s_cselect_b32 s46, s33, s53
	s_add_i32 s38, 0, 0x14000
	ds_read_b128 v[142:145], v0
	ds_read_b128 v[146:149], v0 offset:1024
	ds_read_b128 v[150:153], v0 offset:2048
	ds_read_b128 v[154:157], v0 offset:3072
	v_add_u32_e32 v0, s38, v167
	ds_read_b128 v[158:161], v0
	ds_read_b128 v[162:165], v0 offset:1024
	ds_read_b128 v[172:175], v0 offset:2048
	ds_read_b128 v[176:179], v0 offset:3072
	v_lshl_add_u64 v[218:219], s[48:49], 0, v[138:139]
	s_add_i32 m0, s76, 0xc000
	ds_read_b128 v[180:183], v170
	ds_read_b128 v[184:187], v170 offset:1024
	ds_read_b128 v[188:191], v170 offset:2048
	ds_read_b128 v[192:195], v170 offset:3072
	ds_read_b128 v[202:205], v170 offset:4096
	ds_read_b128 v[206:209], v170 offset:5120
	ds_read_b128 v[210:213], v170 offset:6144
	ds_read_b128 v[214:217], v170 offset:7168
	global_load_lds_dwordx4 v[218:219], off
	v_lshl_add_u64 v[218:219], s[48:49], 0, v[140:141]
	s_add_i32 m0, s76, 0xe000
	s_nop 0
	global_load_lds_dwordx4 v[218:219], off
	s_waitcnt vmcnt(8)
	s_waitcnt lgkmcnt(0)
	s_barrier
	s_setprio 1
	s_waitcnt lgkmcnt(0)
	v_mfma_f32_16x16x32_bf16 v[122:125], v[142:145], v[180:183], v[122:125]
	v_mfma_f32_16x16x32_bf16 v[122:125], v[146:149], v[184:187], v[122:125]
	v_mfma_f32_16x16x32_bf16 v[106:109], v[142:145], v[188:191], v[106:109]
	v_mfma_f32_16x16x32_bf16 v[106:109], v[146:149], v[192:195], v[106:109]
	v_mfma_f32_16x16x32_bf16 v[90:93], v[142:145], v[202:205], v[90:93]
	v_mfma_f32_16x16x32_bf16 v[90:93], v[146:149], v[206:209], v[90:93]
	v_mfma_f32_16x16x32_bf16 v[74:77], v[142:145], v[210:213], v[74:77]
	v_mfma_f32_16x16x32_bf16 v[74:77], v[146:149], v[214:217], v[74:77]
	v_mfma_f32_16x16x32_bf16 v[126:129], v[150:153], v[180:183], v[126:129]
	v_mfma_f32_16x16x32_bf16 v[126:129], v[154:157], v[184:187], v[126:129]
	v_mfma_f32_16x16x32_bf16 v[110:113], v[150:153], v[188:191], v[110:113]
	v_mfma_f32_16x16x32_bf16 v[110:113], v[154:157], v[192:195], v[110:113]
	v_mfma_f32_16x16x32_bf16 v[94:97], v[150:153], v[202:205], v[94:97]
	v_mfma_f32_16x16x32_bf16 v[94:97], v[154:157], v[206:209], v[94:97]
	v_mfma_f32_16x16x32_bf16 v[78:81], v[150:153], v[210:213], v[78:81]
	v_mfma_f32_16x16x32_bf16 v[78:81], v[154:157], v[214:217], v[78:81]
	v_mfma_f32_16x16x32_bf16 v[114:117], v[158:161], v[180:183], v[114:117]
	v_mfma_f32_16x16x32_bf16 v[114:117], v[162:165], v[184:187], v[114:117]
	v_mfma_f32_16x16x32_bf16 v[98:101], v[158:161], v[188:191], v[98:101]
	v_mfma_f32_16x16x32_bf16 v[98:101], v[162:165], v[192:195], v[98:101]
	v_mfma_f32_16x16x32_bf16 v[82:85], v[158:161], v[202:205], v[82:85]
	v_mfma_f32_16x16x32_bf16 v[82:85], v[162:165], v[206:209], v[82:85]
	v_mfma_f32_16x16x32_bf16 v[66:69], v[158:161], v[210:213], v[66:69]
	v_mfma_f32_16x16x32_bf16 v[66:69], v[162:165], v[214:217], v[66:69]
	v_mfma_f32_16x16x32_bf16 v[118:121], v[172:175], v[180:183], v[118:121]
	v_mfma_f32_16x16x32_bf16 v[118:121], v[176:179], v[184:187], v[118:121]
	v_mfma_f32_16x16x32_bf16 v[102:105], v[172:175], v[188:191], v[102:105]
	v_mfma_f32_16x16x32_bf16 v[102:105], v[176:179], v[192:195], v[102:105]
	v_mfma_f32_16x16x32_bf16 v[86:89], v[172:175], v[202:205], v[86:89]
	v_mfma_f32_16x16x32_bf16 v[86:89], v[176:179], v[206:209], v[86:89]
	v_mfma_f32_16x16x32_bf16 v[70:73], v[172:175], v[210:213], v[70:73]
	v_mfma_f32_16x16x32_bf16 v[70:73], v[176:179], v[214:217], v[70:73]
	s_setprio 0
	s_barrier
	s_add_i32 s39, s85, s75
	v_lshl_add_u64 v[218:219], s[46:47], 0, v[134:135]
	s_mov_b32 m0, s39
	ds_read_b128 v[180:183], v170 offset:16384
	ds_read_b128 v[184:187], v170 offset:17408
	ds_read_b128 v[188:191], v170 offset:18432
	ds_read_b128 v[192:195], v170 offset:19456
	ds_read_b128 v[202:205], v170 offset:20480
	ds_read_b128 v[206:209], v170 offset:21504
	ds_read_b128 v[210:213], v170 offset:22528
	ds_read_b128 v[214:217], v170 offset:23552
	global_load_lds_dwordx4 v[218:219], off
	s_add_i32 m0, s39, 0x2000
	s_add_u32 s92, s46, 0x40000
	v_lshl_add_u64 v[220:221], s[46:47], 0, v[130:131]
	s_addc_u32 s93, s47, 0
	s_add_i32 s38, s38, s75
	global_load_lds_dwordx4 v[220:221], off
	v_lshl_add_u64 v[222:223], s[92:93], 0, v[134:135]
	s_mov_b32 m0, s38
	v_lshl_add_u64 v[224:225], s[72:73], 0, v[132:133]
	global_load_lds_dwordx4 v[222:223], off
	v_lshl_add_u64 v[222:223], s[92:93], 0, v[130:131]
	s_add_i32 m0, s38, 0x2000
	s_nop 0
	global_load_lds_dwordx4 v[222:223], off
	v_lshl_add_u64 v[222:223], s[72:73], 0, v[136:137]
	s_mov_b32 m0, s76
	s_nop 0
	global_load_lds_dwordx4 v[222:223], off
	s_mov_b32 m0, s77
	s_nop 0
	global_load_lds_dwordx4 v[224:225], off
	s_waitcnt vmcnt(8)
	s_waitcnt lgkmcnt(0)
	s_barrier
; #define PG8_STAGE(bufoff, gbase, voff) do { _Pragma("unroll") for (int _i = 0; _i < 2; ++_i) \
;         __builtin_amdgcn_global_load_lds((const unsigned*)((const char*)(gbase) + (voff)[_i]), (PG8_LAS unsigned*)(lds + (bufoff) + ldsw + _i * 8192), 16, 0, 0); } while (0)
; #define PG8_LDA(dst, b, h) do { _Pragma("unroll") for (int m = 0; m < 4; ++m) _Pragma("unroll") for (int k = 0; k < 2; ++k) dst[m][k] = *(const PG8_LAS bf16x8*)(lds + PG8_SA(b, h) + aoff + m * 2048 + k * 1024); } while (0)
; #define PG8_LDB(dst, b, h) do { _Pragma("unroll") for (int n = 0; n < 2; ++n) _Pragma("unroll") for (int k = 0; k < 2; ++k) dst[n][k] = *(const PG8_LAS bf16x8*)(lds + PG8_SB(b, h) + boff + n * 2048 + k * 1024); } while (0)
; #define PG8_MMA(ai, bj, At, Bt) do { __builtin_amdgcn_s_setprio(1); _Pragma("unroll") for (int m = 0; m < 4; ++m) _Pragma("unroll") for (int n = 0; n < 2; ++n) _Pragma("unroll") for (int k = 0; k < 2; ++k) \
;         acc[ai][bj][m][n] = __builtin_amdgcn_mfma_f32_16x16x32_bf16(Bt[n][k], At[m][k], acc[ai][bj][m][n], 0, 0, 0); __builtin_amdgcn_s_setprio(0); } while (0)
; #define PG8_WAIT_V(n) asm volatile("s_waitcnt vmcnt(" #n ")" ::: "memory")
; #define PG8_WAIT_L(n) asm volatile("s_waitcnt lgkmcnt(" #n ")" ::: "memory")
; #define PG8_BAR __builtin_amdgcn_s_barrier()
; #define PG8_SCHED __builtin_amdgcn_sched_barrier(0)
; template <class Epi, class Sched, bool ALIGN_EPI = false, bool SP2 = false>
; __device__ __forceinline__ void gemm_phase(PG8_LAS unsigned char* lds, const Gemm g, const Sched& S, const Epi& E) {
;     ...
;             PG8_WAIT_V(8); PG8_WAIT_L(0); PG8_BAR; PG8_MMA(1, 0, At, B0); PG8_MMA(1, 1, At, B1); PG8_BAR; PG8_SCHED;
;             PG8_LDB(B0, 1, 0); PG8_LDB(B1, 1, 1); PG8_SCHED; PG8_LDA(At, 1, 0); PG8_STAGE(PG8_SA(0, 1), a2 + hstep, voffA);
;             PG8_WAIT_V(8); PG8_WAIT_L(0); PG8_BAR; PG8_MMA(0, 0, At, B0); PG8_MMA(0, 1, At, B1); PG8_BAR; PG8_SCHED;
	s_setprio 1
	s_waitcnt lgkmcnt(0)
	v_mfma_f32_16x16x32_bf16 v[58:61], v[142:145], v[180:183], v[58:61]
	v_mfma_f32_16x16x32_bf16 v[58:61], v[146:149], v[184:187], v[58:61]
	v_mfma_f32_16x16x32_bf16 v[42:45], v[142:145], v[188:191], v[42:45]
	v_mfma_f32_16x16x32_bf16 v[42:45], v[146:149], v[192:195], v[42:45]
	v_mfma_f32_16x16x32_bf16 v[26:29], v[142:145], v[202:205], v[26:29]
	v_mfma_f32_16x16x32_bf16 v[26:29], v[146:149], v[206:209], v[26:29]
	v_mfma_f32_16x16x32_bf16 v[10:13], v[142:145], v[210:213], v[10:13]
	v_mfma_f32_16x16x32_bf16 v[10:13], v[146:149], v[214:217], v[10:13]
	v_mfma_f32_16x16x32_bf16 v[62:65], v[150:153], v[180:183], v[62:65]
	v_mfma_f32_16x16x32_bf16 v[62:65], v[154:157], v[184:187], v[62:65]
	v_mfma_f32_16x16x32_bf16 v[46:49], v[150:153], v[188:191], v[46:49]
	v_mfma_f32_16x16x32_bf16 v[46:49], v[154:157], v[192:195], v[46:49]
	v_mfma_f32_16x16x32_bf16 v[30:33], v[150:153], v[202:205], v[30:33]
	v_mfma_f32_16x16x32_bf16 v[30:33], v[154:157], v[206:209], v[30:33]
	v_mfma_f32_16x16x32_bf16 v[14:17], v[150:153], v[210:213], v[14:17]
	v_mfma_f32_16x16x32_bf16 v[14:17], v[154:157], v[214:217], v[14:17]
	v_mfma_f32_16x16x32_bf16 v[50:53], v[158:161], v[180:183], v[50:53]
	v_mfma_f32_16x16x32_bf16 v[50:53], v[162:165], v[184:187], v[50:53]
	v_mfma_f32_16x16x32_bf16 v[34:37], v[158:161], v[188:191], v[34:37]
	v_mfma_f32_16x16x32_bf16 v[34:37], v[162:165], v[192:195], v[34:37]
	v_mfma_f32_16x16x32_bf16 v[18:21], v[158:161], v[202:205], v[18:21]
	v_mfma_f32_16x16x32_bf16 v[18:21], v[162:165], v[206:209], v[18:21]
	v_mfma_f32_16x16x32_bf16 v[2:5], v[158:161], v[210:213], v[2:5]
	v_mfma_f32_16x16x32_bf16 v[2:5], v[162:165], v[214:217], v[2:5]
	v_mfma_f32_16x16x32_bf16 v[54:57], v[172:175], v[180:183], v[54:57]
	v_mfma_f32_16x16x32_bf16 v[54:57], v[176:179], v[184:187], v[54:57]
	v_mfma_f32_16x16x32_bf16 v[38:41], v[172:175], v[188:191], v[38:41]
	v_mfma_f32_16x16x32_bf16 v[38:41], v[176:179], v[192:195], v[38:41]
	v_mfma_f32_16x16x32_bf16 v[22:25], v[172:175], v[202:205], v[22:25]
	v_mfma_f32_16x16x32_bf16 v[22:25], v[176:179], v[206:209], v[22:25]
	v_mfma_f32_16x16x32_bf16 v[6:9], v[172:175], v[210:213], v[6:9]
	v_mfma_f32_16x16x32_bf16 v[6:9], v[176:179], v[214:217], v[6:9]
	s_setprio 0
	s_barrier
	s_add_i32 s38, 0, 0x18000
	v_add_u32_e32 v0, s38, v167
	s_add_i32 s39, 0, 0x1c000
	ds_read_b128 v[142:145], v0
	ds_read_b128 v[146:149], v0 offset:1024
	ds_read_b128 v[150:153], v0 offset:2048
	ds_read_b128 v[154:157], v0 offset:3072
	v_add_u32_e32 v0, s39, v167
	ds_read_b128 v[158:161], v0
	ds_read_b128 v[162:165], v0 offset:1024
	ds_read_b128 v[172:175], v0 offset:2048
	ds_read_b128 v[176:179], v0 offset:3072
	s_add_u32 s72, s72, 0x40000
	s_addc_u32 s73, s73, 0
	s_mov_b32 m0, s78
	v_lshl_add_u64 v[226:227], s[72:73], 0, v[136:137]
	ds_read_b128 v[180:183], v170 offset:32768
	ds_read_b128 v[184:187], v170 offset:33792
	ds_read_b128 v[188:191], v170 offset:34816
	ds_read_b128 v[192:195], v170 offset:35840
	ds_read_b128 v[202:205], v170 offset:36864
	ds_read_b128 v[206:209], v170 offset:37888
	ds_read_b128 v[210:213], v170 offset:38912
	ds_read_b128 v[214:217], v170 offset:39936
	global_load_lds_dwordx4 v[226:227], off
	v_lshl_add_u64 v[226:227], s[72:73], 0, v[132:133]
	s_mov_b32 m0, s79
	s_nop 0
	global_load_lds_dwordx4 v[226:227], off
	s_waitcnt vmcnt(8)
	s_waitcnt lgkmcnt(0)
	s_barrier
	s_setprio 1
	s_waitcnt lgkmcnt(0)
	v_mfma_f32_16x16x32_bf16 v[122:125], v[142:145], v[180:183], v[122:125]
	v_mfma_f32_16x16x32_bf16 v[122:125], v[146:149], v[184:187], v[122:125]
	v_mfma_f32_16x16x32_bf16 v[106:109], v[142:145], v[188:191], v[106:109]
	v_mfma_f32_16x16x32_bf16 v[106:109], v[146:149], v[192:195], v[106:109]
	v_mfma_f32_16x16x32_bf16 v[90:93], v[142:145], v[202:205], v[90:93]
	v_mfma_f32_16x16x32_bf16 v[90:93], v[146:149], v[206:209], v[90:93]
	v_mfma_f32_16x16x32_bf16 v[74:77], v[142:145], v[210:213], v[74:77]
	v_mfma_f32_16x16x32_bf16 v[74:77], v[146:149], v[214:217], v[74:77]
	v_mfma_f32_16x16x32_bf16 v[126:129], v[150:153], v[180:183], v[126:129]
	v_mfma_f32_16x16x32_bf16 v[126:129], v[154:157], v[184:187], v[126:129]
	v_mfma_f32_16x16x32_bf16 v[110:113], v[150:153], v[188:191], v[110:113]
	v_mfma_f32_16x16x32_bf16 v[110:113], v[154:157], v[192:195], v[110:113]
	v_mfma_f32_16x16x32_bf16 v[94:97], v[150:153], v[202:205], v[94:97]
	v_mfma_f32_16x16x32_bf16 v[94:97], v[154:157], v[206:209], v[94:97]
	v_mfma_f32_16x16x32_bf16 v[78:81], v[150:153], v[210:213], v[78:81]
	v_mfma_f32_16x16x32_bf16 v[78:81], v[154:157], v[214:217], v[78:81]
	v_mfma_f32_16x16x32_bf16 v[114:117], v[158:161], v[180:183], v[114:117]
	v_mfma_f32_16x16x32_bf16 v[114:117], v[162:165], v[184:187], v[114:117]
	v_mfma_f32_16x16x32_bf16 v[98:101], v[158:161], v[188:191], v[98:101]
	v_mfma_f32_16x16x32_bf16 v[98:101], v[162:165], v[192:195], v[98:101]
	v_mfma_f32_16x16x32_bf16 v[82:85], v[158:161], v[202:205], v[82:85]
	v_mfma_f32_16x16x32_bf16 v[82:85], v[162:165], v[206:209], v[82:85]
	v_mfma_f32_16x16x32_bf16 v[66:69], v[158:161], v[210:213], v[66:69]
	v_mfma_f32_16x16x32_bf16 v[66:69], v[162:165], v[214:217], v[66:69]
	v_mfma_f32_16x16x32_bf16 v[118:121], v[172:175], v[180:183], v[118:121]
	v_mfma_f32_16x16x32_bf16 v[118:121], v[176:179], v[184:187], v[118:121]
	v_mfma_f32_16x16x32_bf16 v[102:105], v[172:175], v[188:191], v[102:105]
	v_mfma_f32_16x16x32_bf16 v[102:105], v[176:179], v[192:195], v[102:105]
	v_mfma_f32_16x16x32_bf16 v[86:89], v[172:175], v[202:205], v[86:89]
	v_mfma_f32_16x16x32_bf16 v[86:89], v[176:179], v[206:209], v[86:89]
	v_mfma_f32_16x16x32_bf16 v[70:73], v[172:175], v[210:213], v[70:73]
	v_mfma_f32_16x16x32_bf16 v[70:73], v[176:179], v[214:217], v[70:73]
	s_setprio 0
	s_barrier
; #define PG8_STAGE(bufoff, gbase, voff) do { _Pragma("unroll") for (int _i = 0; _i < 2; ++_i) \
;         __builtin_amdgcn_global_load_lds((const unsigned*)((const char*)(gbase) + (voff)[_i]), (PG8_LAS unsigned*)(lds + (bufoff) + ldsw + _i * 8192), 16, 0, 0); } while (0)
; #define PG8_LDA(dst, b, h) do { _Pragma("unroll") for (int m = 0; m < 4; ++m) _Pragma("unroll") for (int k = 0; k < 2; ++k) dst[m][k] = *(const PG8_LAS bf16x8*)(lds + PG8_SA(b, h) + aoff + m * 2048 + k * 1024); } while (0)
; #define PG8_WAIT_V(n) asm volatile("s_waitcnt vmcnt(" #n ")" ::: "memory")
; template <class Epi, class Sched, bool ALIGN_EPI = false, bool SP2 = false>
; __device__ __forceinline__ void gemm_phase(PG8_LAS unsigned char* lds, const Gemm g, const Sched& S, const Epi& E) {
;     ...
;             PG8_LDA(At, 1, 1); PG8_STAGE(PG8_SB(1, 0), b3, voffB); PG8_STAGE(PG8_SB(1, 1), b3 + hstep, voffB); PG8_STAGE(PG8_SA(1, 0), a3, voffA);
;             PG8_WAIT_V(8); PG8_WAIT_L(0); PG8_BAR; PG8_MMA(1, 0, At, B0); PG8_MMA(1, 1, At, B1); PG8_BAR; PG8_SCHED;
;             } else {
;             PG8_LDB(B0, 0, 0); PG8_SCHED; PG8_LDA(At, 0, 0); PG8_STAGE(PG8_SA(1, 1), a1 + hstep, voffA);
;             PG8_WAIT_L(8); PG8_BAR; PG8_WAIT_L(0); PG8_MMA(0, 0, At, B0); PG8_BAR; PG8_SCHED;
;             PG8_LDB(B1, 0, 1); PG8_STAGE(PG8_SB(0, 0), b2, voffB);
;             PG8_BAR; PG8_WAIT_L(0); PG8_MMA(0, 1, At, B1); PG8_BAR;
;             PG8_LDA(At, 0, 1); PG8_STAGE(PG8_SA(0, 0), a2, voffA);
;             PG8_BAR; PG8_WAIT_L(0); PG8_MMA(1, 0, At, B0); PG8_BAR; PG8_SCHED;
;             PG8_STAGE(PG8_SB(0, 1), b2 + hstep, voffB);
;             PG8_WAIT_V(6); PG8_BAR; PG8_MMA(1, 1, At, B1); PG8_BAR;
;             PG8_LDB(B0, 1, 0); PG8_SCHED; PG8_LDA(At, 1, 0); PG8_STAGE(PG8_SA(0, 1), a2 + hstep, voffA);
;             PG8_WAIT_L(8); PG8_BAR; PG8_WAIT_L(0); PG8_MMA(0, 0, At, B0); PG8_BAR; PG8_SCHED;
;             PG8_LDB(B1, 1, 1); PG8_STAGE(PG8_SB(1, 0), b3, voffB);
;             PG8_BAR; PG8_WAIT_L(0); PG8_MMA(0, 1, At, B1); PG8_BAR;
;             PG8_LDA(At, 1, 1); PG8_STAGE(PG8_SA(1, 0), a3, voffA);
;             PG8_BAR; PG8_WAIT_L(0); PG8_MMA(1, 0, At, B0); PG8_BAR; PG8_SCHED;
;             PG8_STAGE(PG8_SB(1, 1), b3 + hstep, voffB);
;             PG8_WAIT_V(6); PG8_BAR; PG8_MMA(1, 1, At, B1); PG8_BAR;
;             }
;         }
;         if constexpr (ALIGN_EPI) { if (wr == 0) PG8_BAR; }
	s_add_i32 s38, s38, s75
	v_lshl_add_u64 v[218:219], v[218:219], 0, s[30:31]
	s_mov_b32 m0, s38
	ds_read_b128 v[180:183], v170 offset:49152
	ds_read_b128 v[184:187], v170 offset:50176
	ds_read_b128 v[188:191], v170 offset:51200
	ds_read_b128 v[192:195], v170 offset:52224
	ds_read_b128 v[202:205], v170 offset:53248
	ds_read_b128 v[206:209], v170 offset:54272
	ds_read_b128 v[210:213], v170 offset:55296
	ds_read_b128 v[214:217], v170 offset:56320
	global_load_lds_dwordx4 v[218:219], off
	s_add_i32 m0, s38, 0x2000
	s_add_u32 s46, s46, 0x40080
	v_lshl_add_u64 v[218:219], v[220:221], 0, s[30:31]
	s_addc_u32 s47, s47, 0
	s_add_i32 s38, s39, s75
	global_load_lds_dwordx4 v[218:219], off
	v_lshl_add_u64 v[218:219], s[46:47], 0, v[134:135]
	s_mov_b32 m0, s38
	s_nop 0
	global_load_lds_dwordx4 v[218:219], off
	v_lshl_add_u64 v[218:219], s[46:47], 0, v[130:131]
	s_add_i32 m0, s38, 0x2000
	s_nop 0
	global_load_lds_dwordx4 v[218:219], off
	v_lshl_add_u64 v[218:219], v[222:223], 0, s[30:31]
	s_mov_b32 m0, s80
	s_nop 0
	global_load_lds_dwordx4 v[218:219], off
	v_lshl_add_u64 v[218:219], v[224:225], 0, s[30:31]
	s_mov_b32 m0, s81
	s_nop 0
	global_load_lds_dwordx4 v[218:219], off
	s_waitcnt vmcnt(8)
	s_waitcnt lgkmcnt(0)
	s_barrier
	s_setprio 1
	s_waitcnt lgkmcnt(0)
	v_mfma_f32_16x16x32_bf16 v[58:61], v[142:145], v[180:183], v[58:61]
	v_mfma_f32_16x16x32_bf16 v[58:61], v[146:149], v[184:187], v[58:61]
	v_mfma_f32_16x16x32_bf16 v[42:45], v[142:145], v[188:191], v[42:45]
	v_mfma_f32_16x16x32_bf16 v[42:45], v[146:149], v[192:195], v[42:45]
	v_mfma_f32_16x16x32_bf16 v[26:29], v[142:145], v[202:205], v[26:29]
	v_mfma_f32_16x16x32_bf16 v[26:29], v[146:149], v[206:209], v[26:29]
	v_mfma_f32_16x16x32_bf16 v[10:13], v[142:145], v[210:213], v[10:13]
	v_mfma_f32_16x16x32_bf16 v[10:13], v[146:149], v[214:217], v[10:13]
	v_mfma_f32_16x16x32_bf16 v[62:65], v[150:153], v[180:183], v[62:65]
	v_mfma_f32_16x16x32_bf16 v[62:65], v[154:157], v[184:187], v[62:65]
	v_mfma_f32_16x16x32_bf16 v[46:49], v[150:153], v[188:191], v[46:49]
	v_mfma_f32_16x16x32_bf16 v[46:49], v[154:157], v[192:195], v[46:49]
	v_mfma_f32_16x16x32_bf16 v[30:33], v[150:153], v[202:205], v[30:33]
	v_mfma_f32_16x16x32_bf16 v[30:33], v[154:157], v[206:209], v[30:33]
	v_mfma_f32_16x16x32_bf16 v[14:17], v[150:153], v[210:213], v[14:17]
	v_mfma_f32_16x16x32_bf16 v[14:17], v[154:157], v[214:217], v[14:17]
	v_mfma_f32_16x16x32_bf16 v[50:53], v[158:161], v[180:183], v[50:53]
	v_mfma_f32_16x16x32_bf16 v[50:53], v[162:165], v[184:187], v[50:53]
	v_mfma_f32_16x16x32_bf16 v[34:37], v[158:161], v[188:191], v[34:37]
	v_mfma_f32_16x16x32_bf16 v[34:37], v[162:165], v[192:195], v[34:37]
	v_mfma_f32_16x16x32_bf16 v[18:21], v[158:161], v[202:205], v[18:21]
	v_mfma_f32_16x16x32_bf16 v[18:21], v[162:165], v[206:209], v[18:21]
	v_mfma_f32_16x16x32_bf16 v[2:5], v[158:161], v[210:213], v[2:5]
	v_mfma_f32_16x16x32_bf16 v[2:5], v[162:165], v[214:217], v[2:5]
	v_mfma_f32_16x16x32_bf16 v[54:57], v[172:175], v[180:183], v[54:57]
	v_mfma_f32_16x16x32_bf16 v[54:57], v[176:179], v[184:187], v[54:57]
	v_mfma_f32_16x16x32_bf16 v[38:41], v[172:175], v[188:191], v[38:41]
	v_mfma_f32_16x16x32_bf16 v[38:41], v[176:179], v[192:195], v[38:41]
	v_mfma_f32_16x16x32_bf16 v[22:25], v[172:175], v[202:205], v[22:25]
	v_mfma_f32_16x16x32_bf16 v[22:25], v[176:179], v[206:209], v[22:25]
	v_mfma_f32_16x16x32_bf16 v[6:9], v[172:175], v[210:213], v[6:9]
	v_mfma_f32_16x16x32_bf16 v[6:9], v[176:179], v[214:217], v[6:9]
	s_setprio 0
	s_barrier
	s_add_i32 s84, s84, 2
	s_add_u32 s48, s48, 0x100
	s_addc_u32 s49, s49, 0
	s_add_u32 s53, s53, 0x100
	s_addc_u32 s69, s69, 0
	s_cmp_gt_u32 s84, 13
	s_cbranch_scc0 .LBB0_408
	s_and_b64 vcc, exec, s[64:65]
	s_cbranch_vccz .LBB0_411
	s_barrier
